# mlstm_pre: the four v-row loads issued before the 32 scattered stores (one counted wait) instead of load/vmcnt(0) per 16 bytes behind them
# baseline (speedup 1.0000x reference)
; DI void conv32(const bf16_t* __restrict__ Pcol, int tok, int spos, const float* wl, int wstride, float* acc) {
; #pragma unroll
;   for (int hq = 0; hq < 2; ++hq) {
;     __builtin_amdgcn_sched_barrier(0);
;     uint4 v[4][2];
; #pragma unroll
;     for (int j = 0; j < 4; ++j) {
;       const bool ok = (spos - 3 + j >= 0);
;       const uint4* src = (const uint4*)(Pcol + (size_t)(tok - 3 + (ok ? j : 3)) * 4096) + 2 * hq;
; #pragma unroll
;       for (int q = 0; q < 2; ++q) {
;         v[j][q] = src[q];
;         if (!ok) v[j][q] = make_uint4(0u, 0u, 0u, 0u);
;       }
;     }
; #pragma unroll
;     for (int i = 0; i < 16; ++i) acc[16 * hq + i] = 0.f;
; #pragma unroll
;     for (int j = 0; j < 4; ++j) {
;       const float4* w4 = (const float4*)(wl + j * wstride + 16 * hq);
; #pragma unroll
;       for (int q = 0; q < 2; ++q) {
;         float f[8];
;         unpack8(v[j][q], f);
;         float4 wa = w4[2 * q], wb = w4[2 * q + 1];
;         float* a = acc + 16 * hq + 8 * q;
;         a[0] += wa.x * f[0]; a[1] += wa.y * f[1]; a[2] += wa.z * f[2]; a[3] += wa.w * f[3];
;         a[4] += wb.x * f[4]; a[5] += wb.y * f[5]; a[6] += wb.z * f[6]; a[7] += wb.w * f[7];
;       }
;     }
; DI void mlstm_pre(const Params& p, int ch, char* smem) {
;     ...
;   const int t = tid >> 2, part = tid & 3;
;   const float wgt = __expf(b_last - s_bc[t] + s_li[t] - m_new);
;   {
;     float a[32];
;     conv32(P + 2048 + h * 128 + part * 32, tok0 + t, c * 64 + t, s_w + part * 32, 256, a);
.LBB0_404:
	s_or_b64 exec, exec, s[10:11]
	s_mul_i32 s9, s44, 0xe000
	s_mul_hi_i32 s8, s44, 0xe000
	s_add_u32 s60, s84, s9
	s_waitcnt vmcnt(63) expcnt(7) lgkmcnt(15)
	s_barrier
	ds_read2st64_b32 v[2:3], v2 offset0:136 offset1:138
	s_addc_u32 s61, s85, s8
	s_add_u32 s66, s60, 0x4000
	s_addc_u32 s67, s61, 0
	s_add_u32 s64, s60, 0x8000
	s_addc_u32 s65, s61, 0
	s_waitcnt lgkmcnt(0)
	v_sub_f32_e32 v0, v0, v3
	s_lshl_b32 s34, s34, 8
	v_add_f32_e32 v0, v0, v2
	s_add_u32 s8, s3, s34
	v_sub_f32_e32 v0, v0, v1
	s_addc_u32 s9, s4, 0
	v_add_u32_e32 v8, s70, v79
	v_mul_f32_e32 v0, 0x3fb8aa3b, v0
	v_lshl_add_u64 v[16:17], s[8:9], 0, v[28:29]
	v_add_u32_e32 v9, s90, v79
	v_add_u32_e32 v18, -3, v8
	v_exp_f32_e32 v83, v0
	v_lshlrev_b32_e32 v84, 7, v81
	v_cmp_lt_i32_e64 s[10:11], 2, v9
	v_cmp_lt_i32_e64 s[12:13], 1, v9
	v_cmp_lt_i32_e64 s[14:15], 0, v9
	v_cndmask_b32_e64 v0, v8, v18, s[10:11]
	v_ashrrev_i32_e32 v1, 31, v0
	v_lshlrev_b64 v[10:11], 13, v[0:1]
	v_lshl_add_u64 v[22:23], v[16:17], 0, v[10:11]
	global_load_dwordx4 v[0:3], v[22:23], off offset:16
	global_load_dwordx4 v[4:7], v[22:23], off
	v_cmp_lt_i32_e64 s[8:9], -1, v9
	v_ashrrev_i32_e32 v9, 31, v8
	v_lshlrev_b64 v[8:9], 13, v[8:9]
	v_lshl_add_u64 v[36:37], v[16:17], 0, v[8:9]
	s_waitcnt vmcnt(1)
	v_cndmask_b32_e64 v35, 0, v0, s[10:11]
	v_cndmask_b32_e64 v0, 3, 1, s[12:13]
	v_add_u32_e32 v0, v0, v18
	v_cndmask_b32_e64 v34, 0, v1, s[10:11]
	v_ashrrev_i32_e32 v1, 31, v0
	s_waitcnt vmcnt(0)
	v_cndmask_b32_e64 v24, 0, v7, s[10:11]
	v_cndmask_b32_e64 v25, 0, v6, s[10:11]
	v_lshlrev_b64 v[6:7], 13, v[0:1]
	v_lshl_add_u64 v[20:21], v[16:17], 0, v[6:7]
	v_cndmask_b32_e64 v32, 0, v3, s[10:11]
	v_cndmask_b32_e64 v33, 0, v2, s[10:11]
	global_load_dwordx4 v[0:3], v[20:21], off offset:16
	global_load_dwordx4 v[12:15], v[20:21], off
	v_cndmask_b32_e64 v26, 0, v5, s[10:11]
	v_cndmask_b32_e64 v27, 0, v4, s[10:11]
	v_lshlrev_b32_e32 v58, 16, v26
	v_and_b32_e32 v59, 0xffff0000, v26
	v_lshlrev_b32_e32 v64, 16, v35
	v_and_b32_e32 v65, 0xffff0000, v35
	v_lshlrev_b32_e32 v86, 16, v34
	v_and_b32_e32 v87, 0xffff0000, v34
	v_lshlrev_b32_e32 v88, 16, v33
	v_and_b32_e32 v89, 0xffff0000, v33
	v_lshlrev_b32_e32 v60, 16, v25
	v_and_b32_e32 v61, 0xffff0000, v25
	v_lshlrev_b32_e32 v62, 16, v24
	v_and_b32_e32 v63, 0xffff0000, v24
	s_waitcnt vmcnt(1)
	v_cndmask_b32_e64 v45, 0, v0, s[12:13]
	v_cndmask_b32_e64 v0, 3, 2, s[14:15]
	v_add_u32_e32 v0, v0, v18
	v_cndmask_b32_e64 v44, 0, v1, s[12:13]
	v_ashrrev_i32_e32 v1, 31, v0
	v_lshlrev_b64 v[4:5], 13, v[0:1]
	v_lshl_add_u64 v[18:19], v[16:17], 0, v[4:5]
	s_waitcnt vmcnt(0)
	v_cndmask_b32_e64 v38, 0, v15, s[12:13]
	v_cndmask_b32_e64 v39, 0, v14, s[12:13]
	v_cndmask_b32_e64 v40, 0, v13, s[12:13]
	v_cndmask_b32_e64 v41, 0, v12, s[12:13]
	v_cndmask_b32_e64 v42, 0, v3, s[12:13]
	v_cndmask_b32_e64 v43, 0, v2, s[12:13]
	global_load_dwordx4 v[0:3], v[18:19], off offset:16
	global_load_dwordx4 v[12:15], v[18:19], off
	v_lshlrev_b32_e32 v16, 16, v27
	v_and_b32_e32 v17, 0xffff0000, v27
	v_lshlrev_b32_e32 v26, 16, v41
	v_and_b32_e32 v27, 0xffff0000, v41
	v_lshlrev_b32_e32 v90, 16, v40
	v_and_b32_e32 v91, 0xffff0000, v40
	v_lshlrev_b32_e32 v92, 16, v39
	v_and_b32_e32 v93, 0xffff0000, v39
	v_lshlrev_b32_e32 v94, 16, v38
	v_and_b32_e32 v95, 0xffff0000, v38
	v_lshlrev_b32_e32 v96, 16, v45
	v_and_b32_e32 v97, 0xffff0000, v45
	v_lshlrev_b32_e32 v98, 16, v44
	v_and_b32_e32 v99, 0xffff0000, v44
	v_lshlrev_b32_e32 v100, 16, v43
	v_and_b32_e32 v101, 0xffff0000, v43
	s_waitcnt vmcnt(1)
	v_cndmask_b32_e64 v50, 0, v3, s[14:15]
	s_waitcnt vmcnt(0)
	v_cndmask_b32_e64 v46, 0, v15, s[14:15]
	v_cndmask_b32_e64 v47, 0, v14, s[14:15]
	v_cndmask_b32_e64 v48, 0, v13, s[14:15]
	v_cndmask_b32_e64 v49, 0, v12, s[14:15]
	v_cndmask_b32_e64 v51, 0, v2, s[14:15]
	v_cndmask_b32_e64 v52, 0, v1, s[14:15]
	v_cndmask_b32_e64 v53, 0, v0, s[14:15]
	global_load_dwordx4 v[0:3], v[36:37], off offset:16
	global_load_dwordx4 v[12:15], v[36:37], off
	v_lshlrev_b32_e32 v54, 16, v49
	v_and_b32_e32 v55, 0xffff0000, v49
	v_lshlrev_b32_e32 v102, 16, v48
	v_and_b32_e32 v103, 0xffff0000, v48
	v_lshlrev_b32_e32 v104, 16, v47
	v_and_b32_e32 v105, 0xffff0000, v47
	v_lshlrev_b32_e32 v106, 16, v46
	v_and_b32_e32 v107, 0xffff0000, v46
	v_lshlrev_b32_e32 v108, 16, v53
	v_and_b32_e32 v109, 0xffff0000, v53
	v_lshlrev_b32_e32 v110, 16, v52
	v_and_b32_e32 v111, 0xffff0000, v52
	v_lshlrev_b32_e32 v112, 16, v51
	v_and_b32_e32 v113, 0xffff0000, v51
	v_lshlrev_b32_e32 v24, 16, v50
	v_and_b32_e32 v25, 0xffff0000, v50
	s_waitcnt vmcnt(1)
	v_cndmask_b32_e64 v122, 0, v3, s[8:9]
	s_waitcnt vmcnt(0)
	v_cndmask_b32_e64 v56, 0, v15, s[8:9]
	v_cndmask_b32_e64 v57, 0, v14, s[8:9]
	v_cndmask_b32_e64 v85, 0, v13, s[8:9]
	v_cndmask_b32_e64 v115, 0, v12, s[8:9]
	v_cndmask_b32_e64 v123, 0, v2, s[8:9]
	v_cndmask_b32_e64 v124, 0, v1, s[8:9]
	v_cndmask_b32_e64 v125, 0, v0, s[8:9]
	v_lshlrev_b32_e32 v12, 16, v32
	v_and_b32_e32 v13, 0xffff0000, v32
	v_lshlrev_b32_e32 v14, 16, v42
	v_and_b32_e32 v15, 0xffff0000, v42
	ds_read_b128 v[32:35], v84 offset:40960
	ds_read_b128 v[38:41], v84 offset:40976
	ds_read_b128 v[42:45], v84 offset:40992
	ds_read_b128 v[0:3], v84 offset:41008
	ds_read_b128 v[46:49], v84 offset:41984
	ds_read_b128 v[50:53], v84 offset:43008
	s_waitcnt lgkmcnt(5)
	v_pk_fma_f32 v[16:17], v[32:33], v[16:17], 0 op_sel_hi:[1,1,0]
	v_lshlrev_b32_e32 v118, 16, v57
	v_and_b32_e32 v119, 0xffff0000, v57
	s_waitcnt lgkmcnt(1)
	v_pk_fma_f32 v[16:17], v[46:47], v[26:27], v[16:17]
	v_lshlrev_b32_e32 v120, 16, v56
	v_and_b32_e32 v121, 0xffff0000, v56
	s_waitcnt lgkmcnt(0)
; DI float sigmoidf_(float x) { return __builtin_amdgcn_rcpf(1.f + __expf(-x)); }
; DI void conv32(const bf16_t* __restrict__ Pcol, int tok, int spos, const float* wl, int wstride, float* acc) {
; #pragma unroll
;   for (int hq = 0; hq < 2; ++hq) {
;     __builtin_amdgcn_sched_barrier(0);
;     uint4 v[4][2];
; #pragma unroll
;     for (int j = 0; j < 4; ++j) {
;       const bool ok = (spos - 3 + j >= 0);
;       const uint4* src = (const uint4*)(Pcol + (size_t)(tok - 3 + (ok ? j : 3)) * 4096) + 2 * hq;
; #pragma unroll
;       for (int q = 0; q < 2; ++q) {
;         v[j][q] = src[q];
;         if (!ok) v[j][q] = make_uint4(0u, 0u, 0u, 0u);
;       }
;     }
; #pragma unroll
;     for (int i = 0; i < 16; ++i) acc[16 * hq + i] = 0.f;
; #pragma unroll
;     for (int j = 0; j < 4; ++j) {
;       const float4* w4 = (const float4*)(wl + j * wstride + 16 * hq);
; #pragma unroll
;       for (int q = 0; q < 2; ++q) {
;         float f[8];
;         unpack8(v[j][q], f);
;         float4 wa = w4[2 * q], wb = w4[2 * q + 1];
;         float* a = acc + 16 * hq + 8 * q;
;         a[0] += wa.x * f[0]; a[1] += wa.y * f[1]; a[2] += wa.z * f[2]; a[3] += wa.w * f[3];
;         a[4] += wb.x * f[4]; a[5] += wb.y * f[5]; a[6] += wb.z * f[6]; a[7] += wb.w * f[7];
;       }
;     }
; #pragma unroll
;     for (int i = 0; i < 16; ++i) acc[16 * hq + i] = acc[16 * hq + i] * sigmoidf_(acc[16 * hq + i]);
;   }
	v_pk_fma_f32 v[16:17], v[50:51], v[54:55], v[16:17]
	ds_read_b128 v[54:57], v84 offset:44032
	v_lshlrev_b32_e32 v114, 16, v115
	v_and_b32_e32 v115, 0xffff0000, v115
	v_pk_fma_f32 v[38:39], v[38:39], v[60:61], 0 op_sel_hi:[1,1,0]
	v_lshlrev_b32_e32 v116, 16, v85
	s_waitcnt lgkmcnt(0)
	v_pk_fma_f32 v[26:27], v[54:55], v[114:115], v[16:17]
	v_pk_fma_f32 v[16:17], v[34:35], v[58:59], 0 op_sel_hi:[1,1,0]
	ds_read_b128 v[32:35], v84 offset:42000
	v_pk_fma_f32 v[16:17], v[48:49], v[90:91], v[16:17]
	ds_read_b128 v[46:49], v84 offset:43024
	v_pk_fma_f32 v[16:17], v[52:53], v[102:103], v[16:17]
	ds_read_b128 v[50:53], v84 offset:44048
	s_waitcnt lgkmcnt(2)
	v_pk_fma_f32 v[32:33], v[32:33], v[92:93], v[38:39]
	v_pk_fma_f32 v[38:39], v[42:43], v[64:65], 0 op_sel_hi:[1,1,0]
	s_waitcnt lgkmcnt(1)
	v_pk_fma_f32 v[32:33], v[46:47], v[104:105], v[32:33]
	v_lshlrev_b32_e32 v54, 16, v125
	s_waitcnt lgkmcnt(0)
	v_pk_fma_f32 v[50:51], v[50:51], v[118:119], v[32:33]
	v_pk_fma_f32 v[32:33], v[40:41], v[62:63], 0 op_sel_hi:[1,1,0]
	v_and_b32_e32 v55, 0xffff0000, v125
	v_pk_fma_f32 v[32:33], v[34:35], v[94:95], v[32:33]
	v_and_b32_e32 v117, 0xffff0000, v85
	v_pk_fma_f32 v[32:33], v[48:49], v[106:107], v[32:33]
	ds_read_b128 v[46:49], v84 offset:44064
	v_pk_fma_f32 v[52:53], v[52:53], v[120:121], v[32:33]
	ds_read_b128 v[32:35], v84 offset:42016
	v_pk_fma_f32 v[16:17], v[56:57], v[116:117], v[16:17]
	v_lshlrev_b32_e32 v56, 16, v124
	v_and_b32_e32 v57, 0xffff0000, v124
	v_pk_fma_f32 v[0:1], v[0:1], v[88:89], 0 op_sel_hi:[1,1,0]
	s_waitcnt lgkmcnt(0)
	v_pk_fma_f32 v[32:33], v[32:33], v[96:97], v[38:39]
	ds_read_b128 v[38:41], v84 offset:43040
	v_lshlrev_b32_e32 v58, 16, v123
	v_and_b32_e32 v59, 0xffff0000, v123
	v_pk_fma_f32 v[2:3], v[2:3], v[12:13], 0 op_sel_hi:[1,1,0]
	v_mul_f32_e32 v12, 0xbfb8aa3b, v26
	s_waitcnt lgkmcnt(0)
	v_pk_fma_f32 v[32:33], v[38:39], v[108:109], v[32:33]
	v_mul_f32_e32 v13, 0xbfb8aa3b, v27
	v_pk_fma_f32 v[54:55], v[46:47], v[54:55], v[32:33]
	v_pk_fma_f32 v[32:33], v[44:45], v[86:87], 0 op_sel_hi:[1,1,0]
	ds_read_b128 v[42:45], v84 offset:43056
	v_pk_fma_f32 v[32:33], v[34:35], v[98:99], v[32:33]
	v_exp_f32_e32 v12, v12
	v_pk_fma_f32 v[32:33], v[40:41], v[110:111], v[32:33]
	ds_read_b128 v[38:41], v84 offset:42032
	v_pk_fma_f32 v[32:33], v[48:49], v[56:57], v[32:33]
	ds_read_b128 v[46:49], v84 offset:44080
	v_mul_f32_e32 v34, 0xbfb8aa3b, v32
	v_mul_f32_e32 v35, 0xbfb8aa3b, v33
	v_exp_f32_e32 v34, v34
	v_exp_f32_e32 v35, v35
	s_waitcnt lgkmcnt(1)
	v_pk_fma_f32 v[0:1], v[38:39], v[100:101], v[0:1]
	v_pk_fma_f32 v[2:3], v[40:41], v[14:15], v[2:3]
	v_add_f32_e32 v34, 1.0, v34
	v_add_f32_e32 v35, 1.0, v35
	v_rcp_f32_e32 v34, v34
	v_rcp_f32_e32 v35, v35
	v_pk_fma_f32 v[0:1], v[42:43], v[112:113], v[0:1]
	v_mul_f32_e32 v14, 0xbfb8aa3b, v16
	s_waitcnt lgkmcnt(0)
	v_pk_fma_f32 v[0:1], v[46:47], v[58:59], v[0:1]
	v_mul_f32_e32 v15, 0xbfb8aa3b, v17
	v_exp_f32_e32 v14, v14
	v_exp_f32_e32 v15, v15
	v_pk_mul_f32 v[32:33], v[32:33], v[34:35]
	v_mul_f32_e32 v34, 0xbfb8aa3b, v0
	v_mul_f32_e32 v35, 0xbfb8aa3b, v1
	v_exp_f32_e32 v13, v13
	v_exp_f32_e32 v34, v34
	v_exp_f32_e32 v35, v35
	v_add_f32_e32 v14, 1.0, v14
	v_add_f32_e32 v15, 1.0, v15
	v_add_f32_e32 v12, 1.0, v12
	v_add_f32_e32 v13, 1.0, v13
	v_rcp_f32_e32 v14, v14
	v_rcp_f32_e32 v15, v15
	v_add_f32_e32 v34, 1.0, v34
	v_add_f32_e32 v35, 1.0, v35
	v_rcp_f32_e32 v12, v12
	v_rcp_f32_e32 v13, v13
	v_rcp_f32_e32 v34, v34
	v_rcp_f32_e32 v35, v35
	v_lshlrev_b32_e32 v60, 16, v122
	v_and_b32_e32 v61, 0xffff0000, v122
	v_pk_fma_f32 v[2:3], v[44:45], v[24:25], v[2:3]
	v_pk_mul_f32 v[14:15], v[16:17], v[14:15]
	v_pk_fma_f32 v[2:3], v[48:49], v[60:61], v[2:3]
	v_mul_f32_e32 v16, 0xbfb8aa3b, v50
	v_mul_f32_e32 v17, 0xbfb8aa3b, v51
	v_mul_f32_e32 v24, 0xbfb8aa3b, v52
	v_mul_f32_e32 v25, 0xbfb8aa3b, v53
	v_pk_mul_f32 v[12:13], v[26:27], v[12:13]
	v_exp_f32_e32 v16, v16
	v_exp_f32_e32 v17, v17
	v_exp_f32_e32 v24, v24
	v_exp_f32_e32 v25, v25
	v_mul_f32_e32 v26, 0xbfb8aa3b, v54
	v_mul_f32_e32 v27, 0xbfb8aa3b, v55
	v_pk_mul_f32 v[34:35], v[0:1], v[34:35]
	v_mul_f32_e32 v0, 0xbfb8aa3b, v2
	v_mul_f32_e32 v1, 0xbfb8aa3b, v3
	v_exp_f32_e32 v26, v26
	v_exp_f32_e32 v27, v27
	v_exp_f32_e32 v0, v0
	v_exp_f32_e32 v1, v1
	v_add_f32_e32 v16, 1.0, v16
	v_add_f32_e32 v17, 1.0, v17
	v_add_f32_e32 v24, 1.0, v24
	v_add_f32_e32 v25, 1.0, v25
	v_rcp_f32_e32 v16, v16
	v_rcp_f32_e32 v17, v17
	v_rcp_f32_e32 v24, v24
	v_rcp_f32_e32 v25, v25
	v_add_f32_e32 v26, 1.0, v26
	v_add_f32_e32 v27, 1.0, v27
	v_add_f32_e32 v0, 1.0, v0
	v_add_f32_e32 v1, 1.0, v1
	v_rcp_f32_e32 v26, v26
	v_rcp_f32_e32 v27, v27
	v_rcp_f32_e32 v0, v0
	v_rcp_f32_e32 v1, v1
	v_pk_mul_f32 v[16:17], v[50:51], v[16:17]
	v_pk_mul_f32 v[24:25], v[52:53], v[24:25]
	v_pk_mul_f32 v[26:27], v[54:55], v[26:27]
	v_pk_mul_f32 v[38:39], v[2:3], v[0:1]
	global_load_dwordx4 v[0:3], v[22:23], off offset:32
	global_load_dwordx4 v[40:43], v[22:23], off offset:48
	global_load_dwordx4 v[44:47], v[20:21], off offset:32
	s_nop 0
	global_load_dwordx4 v[20:23], v[20:21], off offset:48
	s_nop 0
	global_load_dwordx4 v[48:51], v[18:19], off offset:32
	global_load_dwordx4 v[52:55], v[18:19], off offset:48
	global_load_dwordx4 v[56:59], v[36:37], off offset:32
	global_load_dwordx4 v[60:63], v[36:37], off offset:48
	s_waitcnt vmcnt(7)
	v_cndmask_b32_e64 v3, 0, v3, s[10:11]
	v_cndmask_b32_e64 v2, 0, v2, s[10:11]
	v_cndmask_b32_e64 v1, 0, v1, s[10:11]
	v_cndmask_b32_e64 v0, 0, v0, s[10:11]
	s_waitcnt vmcnt(6)
	v_cndmask_b32_e64 v19, 0, v43, s[10:11]
	v_cndmask_b32_e64 v18, 0, v42, s[10:11]
	v_cndmask_b32_e64 v36, 0, v41, s[10:11]
	v_cndmask_b32_e64 v37, 0, v40, s[10:11]
	s_waitcnt vmcnt(5)
; DI float sigmoidf_(float x) { return __builtin_amdgcn_rcpf(1.f + __expf(-x)); }
; DI void conv32(const bf16_t* __restrict__ Pcol, int tok, int spos, const float* wl, int wstride, float* acc) {
; #pragma unroll
;   for (int hq = 0; hq < 2; ++hq) {
;     __builtin_amdgcn_sched_barrier(0);
;     uint4 v[4][2];
; #pragma unroll
;     for (int j = 0; j < 4; ++j) {
;       const bool ok = (spos - 3 + j >= 0);
;       const uint4* src = (const uint4*)(Pcol + (size_t)(tok - 3 + (ok ? j : 3)) * 4096) + 2 * hq;
; #pragma unroll
;       for (int q = 0; q < 2; ++q) {
;         v[j][q] = src[q];
;         if (!ok) v[j][q] = make_uint4(0u, 0u, 0u, 0u);
;       }
;     }
; #pragma unroll
;     for (int i = 0; i < 16; ++i) acc[16 * hq + i] = 0.f;
; #pragma unroll
;     for (int j = 0; j < 4; ++j) {
;       const float4* w4 = (const float4*)(wl + j * wstride + 16 * hq);
; #pragma unroll
;       for (int q = 0; q < 2; ++q) {
;         float f[8];
;         unpack8(v[j][q], f);
;         float4 wa = w4[2 * q], wb = w4[2 * q + 1];
;         float* a = acc + 16 * hq + 8 * q;
;         a[0] += wa.x * f[0]; a[1] += wa.y * f[1]; a[2] += wa.z * f[2]; a[3] += wa.w * f[3];
;         a[4] += wb.x * f[4]; a[5] += wb.y * f[5]; a[6] += wb.z * f[6]; a[7] += wb.w * f[7];
;       }
;     }
; #pragma unroll
;     for (int i = 0; i < 16; ++i) acc[16 * hq + i] = acc[16 * hq + i] * sigmoidf_(acc[16 * hq + i]);
;   }
	v_cndmask_b32_e64 v40, 0, v47, s[12:13]
	v_cndmask_b32_e64 v41, 0, v46, s[12:13]
	v_cndmask_b32_e64 v42, 0, v45, s[12:13]
	v_cndmask_b32_e64 v43, 0, v44, s[12:13]
	s_waitcnt vmcnt(4)
	v_cndmask_b32_e64 v86, 0, v22, s[12:13]
	s_waitcnt vmcnt(3)
	v_cndmask_b32_e64 v87, 0, v51, s[14:15]
	v_cndmask_b32_e64 v88, 0, v50, s[14:15]
	v_cndmask_b32_e64 v89, 0, v49, s[14:15]
	v_cndmask_b32_e64 v90, 0, v48, s[14:15]
	s_waitcnt vmcnt(2)
	v_cndmask_b32_e64 v91, 0, v55, s[14:15]
	v_cndmask_b32_e64 v92, 0, v54, s[14:15]
	s_waitcnt vmcnt(1)
	v_cndmask_b32_e64 v93, 0, v58, s[8:9]
	v_cndmask_b32_e64 v94, 0, v57, s[8:9]
	v_cndmask_b32_e64 v95, 0, v56, s[8:9]
	v_cndmask_b32_e64 v85, 0, v23, s[12:13]
	v_cndmask_b32_e64 v121, 0, v59, s[8:9]
	s_waitcnt vmcnt(0)
	v_cndmask_b32_e64 v64, 0, v63, s[8:9]
	v_cndmask_b32_e64 v65, 0, v62, s[8:9]
	v_cndmask_b32_e64 v122, 0, v61, s[8:9]
	v_cndmask_b32_e64 v123, 0, v60, s[8:9]
	v_lshlrev_b32_e32 v22, 16, v0
	v_and_b32_e32 v23, 0xffff0000, v0
	v_lshlrev_b32_e32 v102, 16, v1
	v_and_b32_e32 v103, 0xffff0000, v1
	v_lshlrev_b32_e32 v106, 16, v2
	v_and_b32_e32 v107, 0xffff0000, v2
	v_lshlrev_b32_e32 v58, 16, v3
	v_and_b32_e32 v59, 0xffff0000, v3
	v_lshlrev_b32_e32 v50, 16, v37
	v_and_b32_e32 v51, 0xffff0000, v37
	v_lshlrev_b32_e32 v46, 16, v36
	v_and_b32_e32 v47, 0xffff0000, v36
	v_lshlrev_b32_e32 v98, 16, v43
	v_and_b32_e32 v99, 0xffff0000, v43
	v_lshlrev_b32_e32 v104, 16, v42
	v_and_b32_e32 v105, 0xffff0000, v42
	v_lshlrev_b32_e32 v108, 16, v41
	v_and_b32_e32 v109, 0xffff0000, v41
	v_lshlrev_b32_e32 v60, 16, v40
	v_and_b32_e32 v61, 0xffff0000, v40
	v_lshlrev_b32_e32 v40, 16, v86
	v_and_b32_e32 v41, 0xffff0000, v86
	v_lshlrev_b32_e32 v100, 16, v90
	v_and_b32_e32 v101, 0xffff0000, v90
	v_lshlrev_b32_e32 v110, 16, v89
	v_and_b32_e32 v111, 0xffff0000, v89
	v_lshlrev_b32_e32 v112, 16, v88
	v_and_b32_e32 v113, 0xffff0000, v88
	v_lshlrev_b32_e32 v62, 16, v87
	v_and_b32_e32 v63, 0xffff0000, v87
	v_lshlrev_b32_e32 v42, 16, v92
	v_and_b32_e32 v43, 0xffff0000, v92
	v_lshlrev_b32_e32 v36, 16, v91
	v_and_b32_e32 v37, 0xffff0000, v91
	v_lshlrev_b32_e32 v114, 16, v95
	v_and_b32_e32 v115, 0xffff0000, v95
	v_lshlrev_b32_e32 v116, 16, v94
	v_and_b32_e32 v117, 0xffff0000, v94
	v_lshlrev_b32_e32 v118, 16, v93
	v_and_b32_e32 v119, 0xffff0000, v93
	ds_read_b128 v[0:3], v84 offset:41024
	ds_read_b128 v[86:89], v84 offset:42048
	ds_read_b128 v[90:93], v84 offset:43072
	ds_read_b128 v[94:97], v84 offset:44096
	v_cndmask_b32_e64 v21, 0, v21, s[12:13]
	s_waitcnt lgkmcnt(3)
	v_pk_fma_f32 v[0:1], v[0:1], v[22:23], 0 op_sel_hi:[1,1,0]
	v_cndmask_b32_e64 v20, 0, v20, s[12:13]
	s_waitcnt lgkmcnt(2)
	v_pk_fma_f32 v[0:1], v[86:87], v[98:99], v[0:1]
	v_cndmask_b32_e64 v55, 0, v53, s[14:15]
	s_waitcnt lgkmcnt(1)
	v_pk_fma_f32 v[0:1], v[90:91], v[100:101], v[0:1]
	ds_read_b128 v[98:101], v84 offset:41040
	s_waitcnt lgkmcnt(1)
	v_pk_fma_f32 v[22:23], v[94:95], v[114:115], v[0:1]
	v_cndmask_b32_e64 v54, 0, v52, s[14:15]
	v_mul_f32_e32 v0, 0xbfb8aa3b, v22
	v_exp_f32_e32 v0, v0
	v_mul_f32_e32 v1, 0xbfb8aa3b, v23
	v_exp_f32_e32 v1, v1
	v_lshlrev_b32_e32 v52, 16, v20
	v_add_f32_e32 v0, 1.0, v0
	v_rcp_f32_e32 v90, v0
	v_add_f32_e32 v0, 1.0, v1
	v_rcp_f32_e32 v91, v0
	v_pk_fma_f32 v[0:1], v[2:3], v[102:103], 0 op_sel_hi:[1,1,0]
	v_and_b32_e32 v53, 0xffff0000, v20
	v_pk_fma_f32 v[0:1], v[88:89], v[104:105], v[0:1]
	v_lshlrev_b32_e32 v48, 16, v21
	v_pk_fma_f32 v[0:1], v[92:93], v[110:111], v[0:1]
	v_and_b32_e32 v49, 0xffff0000, v21
	v_pk_fma_f32 v[110:111], v[96:97], v[116:117], v[0:1]
	v_lshlrev_b32_e32 v20, 16, v85
	v_mul_f32_e32 v0, 0xbfb8aa3b, v110
	v_and_b32_e32 v21, 0xffff0000, v85
	v_exp_f32_e32 v85, v0
	ds_read_b128 v[86:89], v84 offset:41056
	ds_read_b128 v[0:3], v84 offset:41072
	v_pk_mul_f32 v[22:23], v[22:23], v[90:91]
	ds_read_b128 v[90:93], v84 offset:42064
	ds_read_b128 v[94:97], v84 offset:43088
	ds_read_b128 v[102:105], v84 offset:44112
	s_waitcnt lgkmcnt(5)
	v_pk_fma_f32 v[98:99], v[98:99], v[106:107], 0 op_sel_hi:[1,1,0]
	v_pk_fma_f32 v[58:59], v[100:101], v[58:59], 0 op_sel_hi:[1,1,0]
	s_waitcnt lgkmcnt(2)
	v_pk_fma_f32 v[90:91], v[90:91], v[108:109], v[98:99]
	v_add_f32_e32 v85, 1.0, v85
	s_waitcnt lgkmcnt(1)
	v_pk_fma_f32 v[90:91], v[94:95], v[112:113], v[90:91]
	v_pk_fma_f32 v[58:59], v[92:93], v[60:61], v[58:59]
	v_lshlrev_b32_e32 v120, 16, v121
	v_and_b32_e32 v121, 0xffff0000, v121
	v_rcp_f32_e32 v114, v85
	v_mul_f32_e32 v85, 0xbfb8aa3b, v111
	s_waitcnt lgkmcnt(0)
	v_pk_fma_f32 v[98:99], v[102:103], v[118:119], v[90:91]
	v_pk_fma_f32 v[58:59], v[96:97], v[62:63], v[58:59]
	v_exp_f32_e32 v85, v85
	v_mul_f32_e32 v90, 0xbfb8aa3b, v98
	v_pk_fma_f32 v[62:63], v[104:105], v[120:121], v[58:59]
	v_exp_f32_e32 v90, v90
	v_mul_f32_e32 v91, 0xbfb8aa3b, v99
	v_mul_f32_e32 v58, 0xbfb8aa3b, v62
	v_exp_f32_e32 v91, v91
	v_exp_f32_e32 v58, v58
	v_mul_f32_e32 v59, 0xbfb8aa3b, v63
	v_exp_f32_e32 v59, v59
	v_add_f32_e32 v85, 1.0, v85
	v_rcp_f32_e32 v115, v85
	v_add_f32_e32 v85, 1.0, v90
	v_rcp_f32_e32 v102, v85
	v_add_f32_e32 v85, 1.0, v91
	v_add_f32_e32 v58, 1.0, v58
	v_rcp_f32_e32 v103, v85
	v_rcp_f32_e32 v100, v58
	v_add_f32_e32 v85, 1.0, v59
	ds_read_b128 v[58:61], v84 offset:42080
	ds_read_b128 v[90:93], v84 offset:43104
	ds_read_b128 v[94:97], v84 offset:44128
	v_rcp_f32_e32 v101, v85
	v_pk_fma_f32 v[50:51], v[86:87], v[50:51], 0 op_sel_hi:[1,1,0]
	v_lshlrev_b32_e32 v56, 16, v54
	v_and_b32_e32 v57, 0xffff0000, v54
	s_waitcnt lgkmcnt(2)
	v_pk_fma_f32 v[50:51], v[58:59], v[52:53], v[50:51]
	v_pk_fma_f32 v[46:47], v[88:89], v[46:47], 0 op_sel_hi:[1,1,0]
	v_lshlrev_b32_e32 v54, 16, v55
	v_and_b32_e32 v55, 0xffff0000, v55
	s_waitcnt lgkmcnt(1)
; DI int fragoff(int row, int k, int KS) { return (((row >> 4) * KS + (k >> 5)) << 9) + (((((k >> 3) & 3) << 4) + (row & 15)) << 3) + (k & 7); }
; DI void conv32(const bf16_t* __restrict__ Pcol, int tok, int spos, const float* wl, int wstride, float* acc) {
; #pragma unroll
;   for (int hq = 0; hq < 2; ++hq) {
;     __builtin_amdgcn_sched_barrier(0);
;     uint4 v[4][2];
; #pragma unroll
;     for (int j = 0; j < 4; ++j) {
;       const bool ok = (spos - 3 + j >= 0);
;       const uint4* src = (const uint4*)(Pcol + (size_t)(tok - 3 + (ok ? j : 3)) * 4096) + 2 * hq;
; #pragma unroll
;       for (int q = 0; q < 2; ++q) {
;         v[j][q] = src[q];
;         if (!ok) v[j][q] = make_uint4(0u, 0u, 0u, 0u);
;       }
;     }
; DI void mlstm_pre(const Params& p, int ch, char* smem) {
;     ...
; #pragma unroll
;     for (int q = 0; q < 4; ++q) *(uint4*)(qs + t * 136 + part * 32 + 8 * q) = pack8(a + 8 * q);
;     {
;       const float sct = s_sc[t];
; #pragma unroll
;       for (int i = 0; i < 32; ++i) a[i] *= sct;
; #pragma unroll
;       for (int q = 0; q < 4; ++q) *(uint4*)(o_q + fragoff(t, part * 32 + 8 * q, 4)) = pack8(a + 8 * q);
;     }
;     conv32(P + 2560 + h * 128 + part * 32, tok0 + t, c * 64 + t, s_w + 128 + part * 32, 256, a);
	v_pk_fma_f32 v[50:51], v[90:91], v[56:57], v[50:51]
	v_lshlrev_b32_e32 v52, 16, v123
	v_and_b32_e32 v53, 0xffff0000, v123
	v_pk_fma_f32 v[46:47], v[60:61], v[48:49], v[46:47]
	s_waitcnt lgkmcnt(0)
	v_pk_fma_f32 v[58:59], v[94:95], v[52:53], v[50:51]
	v_pk_fma_f32 v[46:47], v[92:93], v[54:55], v[46:47]
	v_lshlrev_b32_e32 v48, 16, v122
	v_and_b32_e32 v49, 0xffff0000, v122
	v_pk_mul_f32 v[56:57], v[62:63], v[100:101]
	v_mul_f32_e32 v63, 0xbfb8aa3b, v59
	v_pk_fma_f32 v[54:55], v[96:97], v[48:49], v[46:47]
	v_mul_f32_e32 v50, 0xbfb8aa3b, v58
	v_exp_f32_e32 v63, v63
	v_mul_f32_e32 v46, 0xbfb8aa3b, v54
	v_exp_f32_e32 v85, v50
	v_exp_f32_e32 v46, v46
	v_add_f32_e32 v47, 1.0, v63
	v_rcp_f32_e32 v91, v47
	v_add_f32_e32 v62, 1.0, v85
	v_add_f32_e32 v46, 1.0, v46
	v_mul_f32_e32 v47, 0xbfb8aa3b, v55
	v_rcp_f32_e32 v90, v62
	v_exp_f32_e32 v85, v47
	v_rcp_f32_e32 v92, v46
	ds_read_b128 v[46:49], v84 offset:42096
	ds_read_b128 v[60:63], v84 offset:43120
	ds_read_b128 v[86:89], v84 offset:44144
	v_lshlrev_b32_e32 v44, 16, v18
	v_and_b32_e32 v45, 0xffff0000, v18
	v_lshlrev_b32_e32 v18, 16, v19
	v_and_b32_e32 v19, 0xffff0000, v19
	v_pk_fma_f32 v[2:3], v[2:3], v[18:19], 0 op_sel_hi:[1,1,0]
	v_pk_fma_f32 v[0:1], v[0:1], v[44:45], 0 op_sel_hi:[1,1,0]
	s_waitcnt lgkmcnt(2)
	v_pk_fma_f32 v[2:3], v[48:49], v[20:21], v[2:3]
	v_pk_fma_f32 v[0:1], v[46:47], v[40:41], v[0:1]
	s_waitcnt lgkmcnt(1)
	v_pk_fma_f32 v[2:3], v[62:63], v[36:37], v[2:3]
	v_lshlrev_b32_e32 v18, 16, v64
	v_and_b32_e32 v19, 0xffff0000, v64
	v_pk_fma_f32 v[0:1], v[60:61], v[42:43], v[0:1]
	v_lshlrev_b32_e32 v40, 16, v65
	v_and_b32_e32 v41, 0xffff0000, v65
	s_waitcnt lgkmcnt(0)
	v_pk_fma_f32 v[2:3], v[88:89], v[18:19], v[2:3]
	v_pk_fma_f32 v[0:1], v[86:87], v[40:41], v[0:1]
	v_mul_f32_e32 v18, 0xbfb8aa3b, v2
	v_mul_f32_e32 v19, 0xbfb8aa3b, v3
	v_mul_f32_e32 v40, 0xbfb8aa3b, v0
	v_mul_f32_e32 v41, 0xbfb8aa3b, v1
	v_exp_f32_e32 v18, v18
	v_exp_f32_e32 v19, v19
	v_exp_f32_e32 v40, v40
	v_exp_f32_e32 v41, v41
	v_add_f32_e32 v18, 1.0, v18
	v_add_f32_e32 v19, 1.0, v19
	v_add_f32_e32 v85, 1.0, v85
	v_add_f32_e32 v40, 1.0, v40
	v_add_f32_e32 v41, 1.0, v41
	v_rcp_f32_e32 v18, v18
	v_rcp_f32_e32 v19, v19
	v_rcp_f32_e32 v93, v85
	v_rcp_f32_e32 v40, v40
	v_rcp_f32_e32 v41, v41
	v_pk_mul_f32 v[20:21], v[58:59], v[90:91]
	v_pk_mul_f32 v[18:19], v[2:3], v[18:19]
	v_pk_mul_f32 v[50:51], v[110:111], v[114:115]
	v_pk_mul_f32 v[52:53], v[98:99], v[102:103]
	v_pk_mul_f32 v[36:37], v[54:55], v[92:93]
	v_pk_mul_f32 v[40:41], v[0:1], v[40:41]
	v_mul_lo_u32 v42, v79, s75
	v_add_u32_e32 v85, v42, v28
	v_cvt_pk_bf16_f32 v0, v12, v13
	v_cvt_pk_bf16_f32 v1, v14, v15
	v_cvt_pk_bf16_f32 v2, v16, v17
	v_cvt_pk_bf16_f32 v3, v24, v25
	ds_write_b128 v85, v[0:3]
	v_cvt_pk_bf16_f32 v0, v26, v27
	v_cvt_pk_bf16_f32 v1, v32, v33
	v_cvt_pk_bf16_f32 v2, v34, v35
	v_cvt_pk_bf16_f32 v3, v38, v39
	ds_write_b128 v85, v[0:3] offset:16
	v_cvt_pk_bf16_f32 v0, v22, v23
	v_cvt_pk_bf16_f32 v1, v50, v51
	v_cvt_pk_bf16_f32 v2, v52, v53
	v_cvt_pk_bf16_f32 v3, v56, v57
	ds_write_b128 v85, v[0:3] offset:32
	v_cvt_pk_bf16_f32 v0, v20, v21
	v_cvt_pk_bf16_f32 v1, v36, v37
	v_cvt_pk_bf16_f32 v2, v40, v41
	v_cvt_pk_bf16_f32 v3, v18, v19
	s_movk_i32 s45, 0xfef4
	ds_write_b128 v85, v[0:3] offset:48
	v_mad_u64_u32 v[0:1], s[70:71], v79, s45, v[42:43]
	ds_read_b32 v0, v0 offset:37408
	s_add_u32 s70, s5, s34
	s_addc_u32 s71, s20, 0
	s_waitcnt lgkmcnt(0)
	v_pk_mul_f32 v[2:3], v[12:13], v[0:1] op_sel_hi:[1,0]
	v_pk_mul_f32 v[12:13], v[14:15], v[0:1] op_sel_hi:[1,0]
	v_pk_mul_f32 v[14:15], v[16:17], v[0:1] op_sel_hi:[1,0]
	v_pk_mul_f32 v[16:17], v[24:25], v[0:1] op_sel_hi:[1,0]
	v_pk_mul_f32 v[24:25], v[26:27], v[0:1] op_sel_hi:[1,0]
	v_pk_mul_f32 v[26:27], v[32:33], v[0:1] op_sel_hi:[1,0]
	v_pk_mul_f32 v[32:33], v[34:35], v[0:1] op_sel_hi:[1,0]
	v_pk_mul_f32 v[34:35], v[38:39], v[0:1] op_sel_hi:[1,0]
	v_pk_mul_f32 v[22:23], v[22:23], v[0:1] op_sel_hi:[1,0]
	v_pk_mul_f32 v[38:39], v[50:51], v[0:1] op_sel_hi:[1,0]
	v_pk_mul_f32 v[42:43], v[52:53], v[0:1] op_sel_hi:[1,0]
	v_pk_mul_f32 v[44:45], v[56:57], v[0:1] op_sel_hi:[1,0]
	v_pk_mul_f32 v[20:21], v[20:21], v[0:1] op_sel_hi:[1,0]
	v_pk_mul_f32 v[36:37], v[36:37], v[0:1] op_sel_hi:[1,0]
	v_pk_mul_f32 v[40:41], v[40:41], v[0:1] op_sel_hi:[1,0]
	v_pk_mul_f32 v[18:19], v[18:19], v[0:1] op_sel_hi:[1,0]
	v_lshrrev_b32_e32 v0, 2, v79
	v_lshlrev_b32_e32 v1, 3, v79
	v_and_or_b32 v0, v0, s76, v81
	v_and_b32_e32 v1, 0x78, v1
	v_lshl_or_b32 v46, v0, 9, v1
	v_ashrrev_i32_e32 v47, 31, v46
	v_cvt_pk_bf16_f32 v0, v2, v3
	v_cvt_pk_bf16_f32 v1, v12, v13
	v_cvt_pk_bf16_f32 v2, v14, v15
	v_cvt_pk_bf16_f32 v3, v16, v17
	v_lshl_add_u64 v[12:13], v[46:47], 1, s[60:61]
	global_store_dwordx4 v[12:13], v[0:3], off
	v_lshl_add_u64 v[16:17], s[70:71], 0, v[28:29]
	s_nop 0
	v_cvt_pk_bf16_f32 v0, v24, v25
	v_cvt_pk_bf16_f32 v1, v26, v27
	v_cvt_pk_bf16_f32 v2, v32, v33
	v_cvt_pk_bf16_f32 v3, v34, v35
	global_store_dwordx4 v[12:13], v[0:3], off offset:256
	s_nop 1
	v_cvt_pk_bf16_f32 v0, v22, v23
	v_cvt_pk_bf16_f32 v1, v38, v39
	v_cvt_pk_bf16_f32 v2, v42, v43
	v_cvt_pk_bf16_f32 v3, v44, v45
	global_store_dwordx4 v[12:13], v[0:3], off offset:512
	s_nop 1
	v_cvt_pk_bf16_f32 v0, v20, v21
	v_cvt_pk_bf16_f32 v1, v36, v37
	v_cvt_pk_bf16_f32 v2, v40, v41
	v_cvt_pk_bf16_f32 v3, v18, v19
	global_store_dwordx4 v[12:13], v[0:3], off offset:768
	v_lshl_add_u64 v[10:11], v[16:17], 0, v[10:11]
	global_load_dwordx4 v[0:3], v[10:11], off offset:16
	global_load_dwordx4 v[12:15], v[10:11], off
	v_lshl_add_u64 v[6:7], v[16:17], 0, v[6:7]
	v_lshl_add_u64 v[4:5], v[16:17], 0, v[4:5]
	s_waitcnt vmcnt(1)
	v_cndmask_b32_e64 v24, 0, v3, s[10:11]
	s_waitcnt vmcnt(0)
; DI float sigmoidf_(float x) { return __builtin_amdgcn_rcpf(1.f + __expf(-x)); }
; DI void conv32(const bf16_t* __restrict__ Pcol, int tok, int spos, const float* wl, int wstride, float* acc) {
;     ...
; #pragma unroll
;     for (int j = 0; j < 4; ++j) {
;       const bool ok = (spos - 3 + j >= 0);
;       const uint4* src = (const uint4*)(Pcol + (size_t)(tok - 3 + (ok ? j : 3)) * 4096) + 2 * hq;
; #pragma unroll
;       for (int q = 0; q < 2; ++q) {
;         v[j][q] = src[q];
;         if (!ok) v[j][q] = make_uint4(0u, 0u, 0u, 0u);
;       }
;     }
; #pragma unroll
;     for (int i = 0; i < 16; ++i) acc[16 * hq + i] = 0.f;
; #pragma unroll
;     for (int j = 0; j < 4; ++j) {
;       const float4* w4 = (const float4*)(wl + j * wstride + 16 * hq);
; #pragma unroll
;       for (int q = 0; q < 2; ++q) {
;         float f[8];
;         unpack8(v[j][q], f);
;         float4 wa = w4[2 * q], wb = w4[2 * q + 1];
;         float* a = acc + 16 * hq + 8 * q;
;         a[0] += wa.x * f[0]; a[1] += wa.y * f[1]; a[2] += wa.z * f[2]; a[3] += wa.w * f[3];
;         a[4] += wb.x * f[4]; a[5] += wb.y * f[5]; a[6] += wb.z * f[6]; a[7] += wb.w * f[7];
;       }
;     }
; #pragma unroll
;     for (int i = 0; i < 16; ++i) acc[16 * hq + i] = acc[16 * hq + i] * sigmoidf_(acc[16 * hq + i]);
	v_cndmask_b32_e64 v20, 0, v15, s[10:11]
	v_cndmask_b32_e64 v21, 0, v14, s[10:11]
	v_cndmask_b32_e64 v23, 0, v13, s[10:11]
	v_cndmask_b32_e64 v19, 0, v12, s[10:11]
	v_cndmask_b32_e64 v25, 0, v2, s[10:11]
	v_cndmask_b32_e64 v26, 0, v1, s[10:11]
	v_cndmask_b32_e64 v27, 0, v0, s[10:11]
	global_load_dwordx4 v[0:3], v[6:7], off offset:16
	global_load_dwordx4 v[12:15], v[6:7], off
	v_lshlrev_b32_e32 v56, 16, v27
	v_and_b32_e32 v57, 0xffff0000, v27
	v_lshlrev_b32_e32 v58, 16, v26
	v_and_b32_e32 v59, 0xffff0000, v26
	v_lshlrev_b32_e32 v60, 16, v25
	v_and_b32_e32 v61, 0xffff0000, v25
	v_lshlrev_b32_e32 v18, 16, v19
	v_and_b32_e32 v19, 0xffff0000, v19
	v_lshlrev_b32_e32 v52, 16, v21
	v_and_b32_e32 v53, 0xffff0000, v21
	v_lshlrev_b32_e32 v54, 16, v20
	v_and_b32_e32 v55, 0xffff0000, v20
	v_lshlrev_b32_e32 v22, 16, v23
	v_and_b32_e32 v23, 0xffff0000, v23
	s_waitcnt vmcnt(1)
	v_cndmask_b32_e64 v36, 0, v3, s[12:13]
	s_waitcnt vmcnt(0)
	v_cndmask_b32_e64 v32, 0, v15, s[12:13]
	v_cndmask_b32_e64 v33, 0, v14, s[12:13]
	v_cndmask_b32_e64 v34, 0, v13, s[12:13]
	v_cndmask_b32_e64 v35, 0, v12, s[12:13]
	v_cndmask_b32_e64 v37, 0, v2, s[12:13]
	v_cndmask_b32_e64 v38, 0, v1, s[12:13]
	v_cndmask_b32_e64 v39, 0, v0, s[12:13]
	global_load_dwordx4 v[0:3], v[4:5], off offset:16
	global_load_dwordx4 v[12:15], v[4:5], off
	v_lshlrev_b32_e32 v44, 16, v35
	v_and_b32_e32 v45, 0xffff0000, v35
	v_lshlrev_b32_e32 v62, 16, v34
	v_and_b32_e32 v63, 0xffff0000, v34
	v_lshlrev_b32_e32 v64, 16, v33
	v_and_b32_e32 v65, 0xffff0000, v33
	v_lshlrev_b32_e32 v86, 16, v32
	v_and_b32_e32 v87, 0xffff0000, v32
	v_lshlrev_b32_e32 v88, 16, v39
	v_and_b32_e32 v89, 0xffff0000, v39
	v_lshlrev_b32_e32 v90, 16, v38
	v_and_b32_e32 v91, 0xffff0000, v38
	v_lshlrev_b32_e32 v92, 16, v37
	v_and_b32_e32 v93, 0xffff0000, v37
	s_waitcnt vmcnt(1)
	v_cndmask_b32_e64 v46, 0, v3, s[14:15]
	s_waitcnt vmcnt(0)
	v_cndmask_b32_e64 v42, 0, v13, s[14:15]
	v_cndmask_b32_e64 v43, 0, v12, s[14:15]
	v_lshl_add_u64 v[12:13], v[16:17], 0, v[8:9]
	v_cndmask_b32_e64 v40, 0, v15, s[14:15]
	v_cndmask_b32_e64 v41, 0, v14, s[14:15]
	v_cndmask_b32_e64 v47, 0, v2, s[14:15]
	v_cndmask_b32_e64 v50, 0, v1, s[14:15]
	v_cndmask_b32_e64 v51, 0, v0, s[14:15]
	global_load_dwordx4 v[0:3], v[12:13], off offset:16
	global_load_dwordx4 v[14:17], v[12:13], off
	v_lshlrev_b32_e32 v48, 16, v43
	v_and_b32_e32 v49, 0xffff0000, v43
	v_lshlrev_b32_e32 v94, 16, v42
	v_and_b32_e32 v95, 0xffff0000, v42
	v_lshlrev_b32_e32 v96, 16, v41
	v_and_b32_e32 v97, 0xffff0000, v41
	v_lshlrev_b32_e32 v98, 16, v40
	v_and_b32_e32 v99, 0xffff0000, v40
	v_lshlrev_b32_e32 v104, 16, v47
	v_and_b32_e32 v105, 0xffff0000, v47
	v_lshlrev_b32_e32 v20, 16, v46
	v_and_b32_e32 v21, 0xffff0000, v46
	v_lshlrev_b32_e32 v100, 16, v51
	v_and_b32_e32 v101, 0xffff0000, v51
	v_lshlrev_b32_e32 v102, 16, v50
	v_and_b32_e32 v103, 0xffff0000, v50
	s_waitcnt vmcnt(1)
	v_cndmask_b32_e64 v114, 0, v3, s[8:9]
	s_waitcnt vmcnt(0)
	v_cndmask_b32_e64 v113, 0, v17, s[8:9]
	v_cndmask_b32_e64 v111, 0, v16, s[8:9]
	v_cndmask_b32_e64 v109, 0, v15, s[8:9]
	v_cndmask_b32_e64 v107, 0, v14, s[8:9]
	v_cndmask_b32_e64 v115, 0, v2, s[8:9]
	v_cndmask_b32_e64 v116, 0, v1, s[8:9]
	v_cndmask_b32_e64 v117, 0, v0, s[8:9]
	v_lshlrev_b32_e32 v14, 16, v24
	v_and_b32_e32 v15, 0xffff0000, v24
	v_lshlrev_b32_e32 v16, 16, v36
	v_and_b32_e32 v17, 0xffff0000, v36
	ds_read_b128 v[24:27], v84 offset:41472
	ds_read_b128 v[32:35], v84 offset:41488
	ds_read_b128 v[36:39], v84 offset:41504
	ds_read_b128 v[0:3], v84 offset:41520
	ds_read_b128 v[40:43], v84 offset:42496
	s_waitcnt lgkmcnt(4)
	v_pk_fma_f32 v[18:19], v[24:25], v[18:19], 0 op_sel_hi:[1,1,0]
	v_lshlrev_b32_e32 v106, 16, v107
	v_and_b32_e32 v107, 0xffff0000, v107
	v_lshlrev_b32_e32 v108, 16, v109
	s_waitcnt lgkmcnt(0)
	v_pk_fma_f32 v[18:19], v[40:41], v[44:45], v[18:19]
	ds_read_b128 v[44:47], v84 offset:43520
	v_and_b32_e32 v109, 0xffff0000, v109
	v_lshlrev_b32_e32 v110, 16, v111
	v_and_b32_e32 v111, 0xffff0000, v111
	v_pk_fma_f32 v[36:37], v[36:37], v[56:57], 0 op_sel_hi:[1,1,0]
	s_waitcnt lgkmcnt(0)
	v_pk_fma_f32 v[18:19], v[44:45], v[48:49], v[18:19]
	ds_read_b128 v[48:51], v84 offset:44544
	v_lshlrev_b32_e32 v112, 16, v113
	v_and_b32_e32 v113, 0xffff0000, v113
	v_pk_fma_f32 v[0:1], v[0:1], v[60:61], 0 op_sel_hi:[1,1,0]
	s_waitcnt lgkmcnt(0)
	v_pk_fma_f32 v[24:25], v[48:49], v[106:107], v[18:19]
	v_pk_fma_f32 v[18:19], v[26:27], v[22:23], 0 op_sel_hi:[1,1,0]
	v_pk_fma_f32 v[22:23], v[32:33], v[52:53], 0 op_sel_hi:[1,1,0]
	v_pk_fma_f32 v[18:19], v[42:43], v[62:63], v[18:19]
	ds_read_b128 v[40:43], v84 offset:42512
	v_pk_fma_f32 v[18:19], v[46:47], v[94:95], v[18:19]
	ds_read_b128 v[44:47], v84 offset:43536
	v_pk_fma_f32 v[18:19], v[50:51], v[108:109], v[18:19]
	ds_read_b128 v[48:51], v84 offset:44560
	s_waitcnt lgkmcnt(2)
	v_pk_fma_f32 v[22:23], v[40:41], v[64:65], v[22:23]
	v_lshlrev_b32_e32 v52, 16, v115
	s_waitcnt lgkmcnt(1)
	v_pk_fma_f32 v[22:23], v[44:45], v[96:97], v[22:23]
	v_and_b32_e32 v53, 0xffff0000, v115
	s_waitcnt lgkmcnt(0)
	v_pk_fma_f32 v[26:27], v[48:49], v[110:111], v[22:23]
	v_pk_fma_f32 v[22:23], v[34:35], v[54:55], 0 op_sel_hi:[1,1,0]
	ds_read_b128 v[32:35], v84 offset:42528
	v_pk_fma_f32 v[22:23], v[42:43], v[86:87], v[22:23]
	ds_read_b128 v[40:43], v84 offset:43552
	v_pk_fma_f32 v[22:23], v[46:47], v[98:99], v[22:23]
	ds_read_b128 v[44:47], v84 offset:44576
	s_waitcnt lgkmcnt(2)
	v_pk_fma_f32 v[32:33], v[32:33], v[88:89], v[36:37]
	v_pk_fma_f32 v[48:49], v[50:51], v[112:113], v[22:23]
	v_lshlrev_b32_e32 v22, 16, v117
	v_and_b32_e32 v23, 0xffff0000, v117
	s_waitcnt lgkmcnt(1)
	v_pk_fma_f32 v[32:33], v[40:41], v[100:101], v[32:33]
	v_lshlrev_b32_e32 v54, 16, v114
	s_waitcnt lgkmcnt(0)
; DI float sigmoidf_(float x) { return __builtin_amdgcn_rcpf(1.f + __expf(-x)); }
; DI void conv32(const bf16_t* __restrict__ Pcol, int tok, int spos, const float* wl, int wstride, float* acc) {
;     ...
; #pragma unroll
;     for (int j = 0; j < 4; ++j) {
;       const bool ok = (spos - 3 + j >= 0);
;       const uint4* src = (const uint4*)(Pcol + (size_t)(tok - 3 + (ok ? j : 3)) * 4096) + 2 * hq;
; #pragma unroll
;       for (int q = 0; q < 2; ++q) {
;         v[j][q] = src[q];
;         if (!ok) v[j][q] = make_uint4(0u, 0u, 0u, 0u);
;       }
;     }
; #pragma unroll
;     for (int i = 0; i < 16; ++i) acc[16 * hq + i] = 0.f;
; #pragma unroll
;     for (int j = 0; j < 4; ++j) {
;       const float4* w4 = (const float4*)(wl + j * wstride + 16 * hq);
; #pragma unroll
;       for (int q = 0; q < 2; ++q) {
;         float f[8];
;         unpack8(v[j][q], f);
;         float4 wa = w4[2 * q], wb = w4[2 * q + 1];
;         float* a = acc + 16 * hq + 8 * q;
;         a[0] += wa.x * f[0]; a[1] += wa.y * f[1]; a[2] += wa.z * f[2]; a[3] += wa.w * f[3];
;         a[4] += wb.x * f[4]; a[5] += wb.y * f[5]; a[6] += wb.z * f[6]; a[7] += wb.w * f[7];
;       }
;     }
; #pragma unroll
;     for (int i = 0; i < 16; ++i) acc[16 * hq + i] = acc[16 * hq + i] * sigmoidf_(acc[16 * hq + i]);
	v_pk_fma_f32 v[44:45], v[44:45], v[22:23], v[32:33]
	v_pk_fma_f32 v[22:23], v[38:39], v[58:59], 0 op_sel_hi:[1,1,0]
	ds_read_b128 v[36:39], v84 offset:43568
	v_pk_fma_f32 v[22:23], v[34:35], v[90:91], v[22:23]
	ds_read_b128 v[32:35], v84 offset:42544
	v_pk_fma_f32 v[22:23], v[42:43], v[102:103], v[22:23]
	ds_read_b128 v[40:43], v84 offset:44592
	v_and_b32_e32 v55, 0xffff0000, v114
	v_lshlrev_b32_e32 v50, 16, v116
	s_waitcnt lgkmcnt(1)
	v_pk_fma_f32 v[0:1], v[32:33], v[92:93], v[0:1]
	v_and_b32_e32 v51, 0xffff0000, v116
	v_pk_fma_f32 v[0:1], v[36:37], v[104:105], v[0:1]
	v_pk_fma_f32 v[22:23], v[46:47], v[50:51], v[22:23]
	s_waitcnt lgkmcnt(0)
	v_pk_fma_f32 v[32:33], v[40:41], v[52:53], v[0:1]
	v_pk_fma_f32 v[0:1], v[2:3], v[14:15], 0 op_sel_hi:[1,1,0]
	v_mul_f32_e32 v2, 0xbfb8aa3b, v18
	v_pk_fma_f32 v[0:1], v[34:35], v[16:17], v[0:1]
	v_mul_f32_e32 v3, 0xbfb8aa3b, v19
	v_pk_fma_f32 v[0:1], v[38:39], v[20:21], v[0:1]
	v_exp_f32_e32 v2, v2
	v_pk_fma_f32 v[20:21], v[42:43], v[54:55], v[0:1]
	v_mul_f32_e32 v0, 0xbfb8aa3b, v24
	v_mul_f32_e32 v1, 0xbfb8aa3b, v25
	v_exp_f32_e32 v0, v0
	v_exp_f32_e32 v1, v1
	v_exp_f32_e32 v3, v3
	v_add_f32_e32 v2, 1.0, v2
	v_add_f32_e32 v0, 1.0, v0
	v_add_f32_e32 v1, 1.0, v1
	v_rcp_f32_e32 v0, v0
	v_rcp_f32_e32 v1, v1
	v_add_f32_e32 v3, 1.0, v3
	v_rcp_f32_e32 v2, v2
	v_rcp_f32_e32 v3, v3
	v_pk_mul_f32 v[0:1], v[24:25], v[0:1]
	v_mul_f32_e32 v24, 0xbfb8aa3b, v22
	v_mul_f32_e32 v25, 0xbfb8aa3b, v23
	v_exp_f32_e32 v24, v24
	v_exp_f32_e32 v25, v25
	v_pk_mul_f32 v[2:3], v[18:19], v[2:3]
	v_mul_f32_e32 v14, 0xbfb8aa3b, v26
	v_add_f32_e32 v24, 1.0, v24
	v_add_f32_e32 v25, 1.0, v25
	v_rcp_f32_e32 v24, v24
	v_rcp_f32_e32 v25, v25
	v_mul_f32_e32 v15, 0xbfb8aa3b, v27
	v_mul_f32_e32 v16, 0xbfb8aa3b, v48
	v_mul_f32_e32 v17, 0xbfb8aa3b, v49
	v_pk_mul_f32 v[64:65], v[22:23], v[24:25]
	v_mul_f32_e32 v22, 0xbfb8aa3b, v32
	v_mul_f32_e32 v23, 0xbfb8aa3b, v33
	v_exp_f32_e32 v22, v22
	v_exp_f32_e32 v23, v23
	v_mul_f32_e32 v18, 0xbfb8aa3b, v44
	v_mul_f32_e32 v19, 0xbfb8aa3b, v45
	v_add_f32_e32 v22, 1.0, v22
	v_add_f32_e32 v23, 1.0, v23
	v_rcp_f32_e32 v22, v22
	v_rcp_f32_e32 v23, v23
	v_exp_f32_e32 v14, v14
	v_exp_f32_e32 v15, v15
	v_exp_f32_e32 v16, v16
	v_exp_f32_e32 v17, v17
	v_exp_f32_e32 v18, v18
	v_exp_f32_e32 v19, v19
	v_pk_mul_f32 v[88:89], v[32:33], v[22:23]
	v_mul_f32_e32 v22, 0xbfb8aa3b, v20
	v_mul_f32_e32 v23, 0xbfb8aa3b, v21
	v_exp_f32_e32 v22, v22
	v_exp_f32_e32 v23, v23
	v_add_f32_e32 v14, 1.0, v14
	v_add_f32_e32 v15, 1.0, v15
	v_add_f32_e32 v16, 1.0, v16
	v_add_f32_e32 v17, 1.0, v17
	v_add_f32_e32 v18, 1.0, v18
	v_add_f32_e32 v19, 1.0, v19
	v_rcp_f32_e32 v14, v14
	v_rcp_f32_e32 v15, v15
	v_rcp_f32_e32 v16, v16
	v_rcp_f32_e32 v17, v17
	v_rcp_f32_e32 v18, v18
	v_rcp_f32_e32 v19, v19
	v_add_f32_e32 v22, 1.0, v22
	v_add_f32_e32 v23, 1.0, v23
	v_rcp_f32_e32 v22, v22
	v_rcp_f32_e32 v23, v23
	v_pk_mul_f32 v[14:15], v[26:27], v[14:15]
	v_pk_mul_f32 v[16:17], v[48:49], v[16:17]
	v_pk_mul_f32 v[18:19], v[44:45], v[18:19]
	v_pk_mul_f32 v[90:91], v[20:21], v[22:23]
	global_load_dwordx4 v[20:23], v[10:11], off offset:32
	global_load_dwordx4 v[24:27], v[10:11], off offset:48
	global_load_dwordx4 v[32:35], v[6:7], off offset:32
	global_load_dwordx4 v[36:39], v[6:7], off offset:48
	global_load_dwordx4 v[40:43], v[4:5], off offset:32
	s_nop 0
	global_load_dwordx4 v[4:7], v[4:5], off offset:48
	s_nop 0
	global_load_dwordx4 v[44:47], v[12:13], off offset:32
	s_nop 0
	global_load_dwordx4 v[10:13], v[12:13], off offset:48
	v_pk_mul_f32 v[18:19], v[18:19], s[36:37] op_sel_hi:[1,0]
	s_waitcnt vmcnt(7)
	v_cndmask_b32_e64 v20, 0, v20, s[10:11]
	s_waitcnt vmcnt(6)
	v_cndmask_b32_e64 v27, 0, v27, s[10:11]
	v_cndmask_b32_e64 v26, 0, v26, s[10:11]
	v_cndmask_b32_e64 v25, 0, v25, s[10:11]
	v_cndmask_b32_e64 v24, 0, v24, s[10:11]
	s_waitcnt vmcnt(5)
	v_cndmask_b32_e64 v52, 0, v35, s[12:13]
	v_cndmask_b32_e64 v53, 0, v34, s[12:13]
	v_cndmask_b32_e64 v54, 0, v33, s[12:13]
	v_cndmask_b32_e64 v55, 0, v32, s[12:13]
	s_waitcnt vmcnt(4)
	v_cndmask_b32_e64 v56, 0, v39, s[12:13]
	v_cndmask_b32_e64 v57, 0, v38, s[12:13]
	v_cndmask_b32_e64 v37, 0, v37, s[12:13]
	v_cndmask_b32_e64 v36, 0, v36, s[12:13]
	s_waitcnt vmcnt(3)
	v_cndmask_b32_e64 v41, 0, v41, s[14:15]
	v_cndmask_b32_e64 v40, 0, v40, s[14:15]
	s_waitcnt vmcnt(2)
	v_cndmask_b32_e64 v62, 0, v7, s[14:15]
	v_cndmask_b32_e64 v63, 0, v6, s[14:15]
	v_cndmask_b32_e64 v92, 0, v5, s[14:15]
	v_cndmask_b32_e64 v93, 0, v4, s[14:15]
	s_waitcnt vmcnt(1)
	v_cndmask_b32_e64 v94, 0, v47, s[8:9]
	v_cndmask_b32_e64 v95, 0, v46, s[8:9]
	v_cndmask_b32_e64 v96, 0, v45, s[8:9]
	v_cndmask_b32_e64 v97, 0, v44, s[8:9]
	v_cndmask_b32_e64 v61, 0, v43, s[14:15]
	v_cndmask_b32_e64 v60, 0, v42, s[14:15]
	s_waitcnt vmcnt(0)
; DI float sigmoidf_(float x) { return __builtin_amdgcn_rcpf(1.f + __expf(-x)); }
; DI void conv32(const bf16_t* __restrict__ Pcol, int tok, int spos, const float* wl, int wstride, float* acc) {
;     ...
; #pragma unroll
;     for (int j = 0; j < 4; ++j) {
;       const bool ok = (spos - 3 + j >= 0);
;       const uint4* src = (const uint4*)(Pcol + (size_t)(tok - 3 + (ok ? j : 3)) * 4096) + 2 * hq;
; #pragma unroll
;       for (int q = 0; q < 2; ++q) {
;         v[j][q] = src[q];
;         if (!ok) v[j][q] = make_uint4(0u, 0u, 0u, 0u);
;       }
;     }
; #pragma unroll
;     for (int i = 0; i < 16; ++i) acc[16 * hq + i] = 0.f;
; #pragma unroll
;     for (int j = 0; j < 4; ++j) {
;       const float4* w4 = (const float4*)(wl + j * wstride + 16 * hq);
; #pragma unroll
;       for (int q = 0; q < 2; ++q) {
;         float f[8];
;         unpack8(v[j][q], f);
;         float4 wa = w4[2 * q], wb = w4[2 * q + 1];
;         float* a = acc + 16 * hq + 8 * q;
;         a[0] += wa.x * f[0]; a[1] += wa.y * f[1]; a[2] += wa.z * f[2]; a[3] += wa.w * f[3];
;         a[4] += wb.x * f[4]; a[5] += wb.y * f[5]; a[6] += wb.z * f[6]; a[7] += wb.w * f[7];
;       }
;     }
; #pragma unroll
;     for (int i = 0; i < 16; ++i) acc[16 * hq + i] = acc[16 * hq + i] * sigmoidf_(acc[16 * hq + i]);
	v_cndmask_b32_e64 v86, 0, v13, s[8:9]
	v_cndmask_b32_e64 v87, 0, v12, s[8:9]
	v_cndmask_b32_e64 v124, 0, v11, s[8:9]
	v_cndmask_b32_e64 v125, 0, v10, s[8:9]
	v_lshlrev_b32_e32 v4, 16, v20
	v_and_b32_e32 v5, 0xffff0000, v20
	v_lshlrev_b32_e32 v38, 16, v24
	v_and_b32_e32 v39, 0xffff0000, v24
	v_lshlrev_b32_e32 v50, 16, v25
	v_and_b32_e32 v51, 0xffff0000, v25
	v_lshlrev_b32_e32 v48, 16, v26
	v_and_b32_e32 v49, 0xffff0000, v26
	v_lshlrev_b32_e32 v32, 16, v27
	v_and_b32_e32 v33, 0xffff0000, v27
	v_lshlrev_b32_e32 v6, 16, v55
	v_and_b32_e32 v7, 0xffff0000, v55
	v_lshlrev_b32_e32 v108, 16, v54
	v_and_b32_e32 v109, 0xffff0000, v54
	v_lshlrev_b32_e32 v110, 16, v53
	v_and_b32_e32 v111, 0xffff0000, v53
	v_lshlrev_b32_e32 v58, 16, v52
	v_and_b32_e32 v59, 0xffff0000, v52
	v_lshlrev_b32_e32 v42, 16, v36
	v_and_b32_e32 v43, 0xffff0000, v36
	v_lshlrev_b32_e32 v52, 16, v37
	v_and_b32_e32 v53, 0xffff0000, v37
	v_lshlrev_b32_e32 v44, 16, v57
	v_and_b32_e32 v45, 0xffff0000, v57
	v_lshlrev_b32_e32 v36, 16, v56
	v_and_b32_e32 v37, 0xffff0000, v56
	v_lshlrev_b32_e32 v112, 16, v40
	v_and_b32_e32 v113, 0xffff0000, v40
	v_lshlrev_b32_e32 v114, 16, v41
	v_and_b32_e32 v115, 0xffff0000, v41
	v_lshlrev_b32_e32 v56, 16, v93
	v_and_b32_e32 v57, 0xffff0000, v93
	v_lshlrev_b32_e32 v54, 16, v92
	v_and_b32_e32 v55, 0xffff0000, v92
	v_lshlrev_b32_e32 v46, 16, v63
	v_and_b32_e32 v47, 0xffff0000, v63
	v_lshlrev_b32_e32 v40, 16, v62
	v_and_b32_e32 v41, 0xffff0000, v62
	v_lshlrev_b32_e32 v118, 16, v97
	v_and_b32_e32 v119, 0xffff0000, v97
	v_lshlrev_b32_e32 v120, 16, v96
	v_and_b32_e32 v121, 0xffff0000, v96
	v_lshlrev_b32_e32 v122, 16, v95
	v_and_b32_e32 v123, 0xffff0000, v95
	v_lshlrev_b32_e32 v62, 16, v94
	v_and_b32_e32 v63, 0xffff0000, v94
	v_pk_mul_f32 v[26:27], v[0:1], s[36:37] op_sel_hi:[1,0]
	v_pk_mul_f32 v[24:25], v[2:3], s[36:37] op_sel_hi:[1,0]
	v_pk_mul_f32 v[12:13], v[88:89], s[36:37] op_sel_hi:[1,0]
	v_pk_mul_f32 v[10:11], v[90:91], s[36:37] op_sel_hi:[1,0]
	ds_read_b128 v[0:3], v84 offset:41536
	ds_read_b128 v[88:91], v84 offset:42560
	ds_read_b128 v[92:95], v84 offset:43584
	ds_read_b128 v[96:99], v84 offset:44608
	ds_read_b128 v[100:103], v84 offset:41552
	s_waitcnt lgkmcnt(4)
	v_pk_fma_f32 v[0:1], v[0:1], v[4:5], 0 op_sel_hi:[1,1,0]
	v_cndmask_b32_e64 v23, 0, v23, s[10:11]
	s_waitcnt lgkmcnt(3)
	v_pk_fma_f32 v[0:1], v[88:89], v[6:7], v[0:1]
	v_cndmask_b32_e64 v22, 0, v22, s[10:11]
	s_waitcnt lgkmcnt(2)
	v_pk_fma_f32 v[0:1], v[92:93], v[112:113], v[0:1]
	v_lshlrev_b32_e32 v106, 16, v22
	v_and_b32_e32 v107, 0xffff0000, v22
	v_lshlrev_b32_e32 v34, 16, v23
	v_and_b32_e32 v35, 0xffff0000, v23
	v_pk_mul_f32 v[22:23], v[14:15], s[36:37] op_sel_hi:[1,0]
	s_waitcnt lgkmcnt(1)
	v_pk_fma_f32 v[14:15], v[96:97], v[118:119], v[0:1]
	v_cndmask_b32_e64 v21, 0, v21, s[10:11]
	v_mul_f32_e32 v0, 0xbfb8aa3b, v14
	v_exp_f32_e32 v0, v0
	v_mul_f32_e32 v1, 0xbfb8aa3b, v15
	v_exp_f32_e32 v1, v1
	v_lshlrev_b32_e32 v104, 16, v21
	v_add_f32_e32 v0, 1.0, v0
	v_and_b32_e32 v105, 0xffff0000, v21
	v_pk_mul_f32 v[20:21], v[16:17], s[36:37] op_sel_hi:[1,0]
	v_pk_mul_f32 v[16:17], v[64:65], s[36:37] op_sel_hi:[1,0]
	v_rcp_f32_e32 v64, v0
	v_add_f32_e32 v0, 1.0, v1
	v_rcp_f32_e32 v65, v0
	v_pk_fma_f32 v[0:1], v[2:3], v[104:105], 0 op_sel_hi:[1,1,0]
	ds_read_b128 v[4:7], v84 offset:41568
	v_pk_fma_f32 v[0:1], v[90:91], v[108:109], v[0:1]
	v_pk_mul_f32 v[14:15], v[14:15], v[64:65]
	v_pk_fma_f32 v[0:1], v[94:95], v[114:115], v[0:1]
	s_waitcnt lgkmcnt(1)
	v_pk_fma_f32 v[100:101], v[100:101], v[106:107], 0 op_sel_hi:[1,1,0]
	v_pk_fma_f32 v[104:105], v[98:99], v[120:121], v[0:1]
	v_lshlrev_b32_e32 v116, 16, v60
	v_mul_f32_e32 v0, 0xbfb8aa3b, v104
	v_exp_f32_e32 v88, v0
	ds_read_b128 v[0:3], v84 offset:41584
	v_and_b32_e32 v117, 0xffff0000, v60
	v_mul_f32_e32 v65, 0xbfb8aa3b, v105
	v_add_f32_e32 v64, 1.0, v88
	ds_read_b128 v[88:91], v84 offset:42576
	ds_read_b128 v[92:95], v84 offset:43600
	ds_read_b128 v[96:99], v84 offset:44624
	v_pk_fma_f32 v[34:35], v[102:103], v[34:35], 0 op_sel_hi:[1,1,0]
	v_lshlrev_b32_e32 v60, 16, v61
	s_waitcnt lgkmcnt(2)
	v_pk_fma_f32 v[88:89], v[88:89], v[110:111], v[100:101]
	v_and_b32_e32 v61, 0xffff0000, v61
	s_waitcnt lgkmcnt(1)
	v_pk_fma_f32 v[88:89], v[92:93], v[116:117], v[88:89]
	v_exp_f32_e32 v65, v65
	s_waitcnt lgkmcnt(0)
	v_pk_fma_f32 v[88:89], v[96:97], v[122:123], v[88:89]
	v_pk_fma_f32 v[34:35], v[90:91], v[58:59], v[34:35]
	v_mul_f32_e32 v92, 0xbfb8aa3b, v88
	v_mul_f32_e32 v93, 0xbfb8aa3b, v89
	v_exp_f32_e32 v92, v92
	v_exp_f32_e32 v93, v93
	v_pk_fma_f32 v[34:35], v[94:95], v[60:61], v[34:35]
	v_add_f32_e32 v65, 1.0, v65
	v_add_f32_e32 v92, 1.0, v92
	v_add_f32_e32 v93, 1.0, v93
	v_rcp_f32_e32 v92, v92
	v_rcp_f32_e32 v93, v93
	v_pk_fma_f32 v[94:95], v[98:99], v[62:63], v[34:35]
	v_rcp_f32_e32 v64, v64
	v_mul_f32_e32 v34, 0xbfb8aa3b, v94
	v_exp_f32_e32 v58, v34
	v_rcp_f32_e32 v65, v65
	v_mul_f32_e32 v59, 0xbfb8aa3b, v95
	v_pk_mul_f32 v[92:93], v[88:89], v[92:93]
	v_exp_f32_e32 v88, v59
	v_add_f32_e32 v58, 1.0, v58
	v_pk_mul_f32 v[34:35], v[104:105], v[64:65]
	v_rcp_f32_e32 v96, v58
	ds_read_b128 v[58:61], v84 offset:42592
	ds_read_b128 v[62:65], v84 offset:43616
	v_add_f32_e32 v97, 1.0, v88
	ds_read_b128 v[88:91], v84 offset:44640
	v_pk_fma_f32 v[4:5], v[4:5], v[38:39], 0 op_sel_hi:[1,1,0]
	v_lshlrev_b32_e32 v38, 16, v125
	s_waitcnt lgkmcnt(2)
	v_pk_fma_f32 v[4:5], v[58:59], v[42:43], v[4:5]
	v_and_b32_e32 v39, 0xffff0000, v125
	s_waitcnt lgkmcnt(1)
	v_pk_fma_f32 v[4:5], v[62:63], v[56:57], v[4:5]
	v_pk_fma_f32 v[6:7], v[6:7], v[50:51], 0 op_sel_hi:[1,1,0]
	s_waitcnt lgkmcnt(0)
; DI bf16_t f2bf(float f) { return (bf16_t)(pk2(f, 0.f) & 0xffffu); }
; DI float bf2f(bf16_t h) { return __uint_as_float(((unsigned)h) << 16); }
; DI int fragoff(int row, int k, int KS) { return (((row >> 4) * KS + (k >> 5)) << 9) + (((((k >> 3) & 3) << 4) + (row & 15)) << 3) + (k & 7); }
; DI void mlstm_pre(const Params& p, int ch, char* smem) {
;     ...
;     for (int i = 0; i < 32; ++i) a[i] *= 0.08838834764831845f;
; #pragma unroll
;     for (int q = 0; q < 4; ++q) *(uint4*)(ks + t * 136 + part * 32 + 8 * q) = pack8(a + 8 * q);
; #pragma unroll
;     for (int i = 0; i < 32; ++i) {
;       bf16_t kb = f2bf(a[i] * wgt);
;       o_kwT[fragoff(part * 32 + i, t, 2)] = kb;
;       atomicAdd(&s_kw[part * 32 + i], bf2f(kb));
;     }
;     const uint4* vsrc = (const uint4*)(P + (size_t)(tok0 + t) * 4096 + 3072 + h * 128 + part * 32);
; #pragma unroll
;     for (int q = 0; q < 4; ++q) {
;       uint4 v = vsrc[q];
	v_pk_fma_f32 v[4:5], v[88:89], v[38:39], v[4:5]
	v_pk_fma_f32 v[6:7], v[60:61], v[52:53], v[6:7]
	v_mul_f32_e32 v38, 0xbfb8aa3b, v4
	v_exp_f32_e32 v38, v38
	v_mul_f32_e32 v39, 0xbfb8aa3b, v5
	v_exp_f32_e32 v39, v39
	v_pk_fma_f32 v[6:7], v[64:65], v[54:55], v[6:7]
	v_lshlrev_b32_e32 v50, 16, v124
	v_and_b32_e32 v51, 0xffff0000, v124
	v_pk_fma_f32 v[6:7], v[90:91], v[50:51], v[6:7]
	v_add_f32_e32 v38, 1.0, v38
	v_mul_f32_e32 v50, 0xbfb8aa3b, v6
	v_rcp_f32_e32 v56, v38
	v_add_f32_e32 v38, 1.0, v39
	v_exp_f32_e32 v50, v50
	v_mul_f32_e32 v51, 0xbfb8aa3b, v7
	v_rcp_f32_e32 v57, v38
	v_exp_f32_e32 v51, v51
	v_add_f32_e32 v50, 1.0, v50
	v_rcp_f32_e32 v62, v50
	v_pk_mul_f32 v[4:5], v[4:5], v[56:57]
	v_add_f32_e32 v58, 1.0, v51
	ds_read_b128 v[50:53], v84 offset:42608
	ds_read_b128 v[54:57], v84 offset:43632
	v_rcp_f32_e32 v63, v58
	ds_read_b128 v[58:61], v84 offset:44656
	v_pk_fma_f32 v[0:1], v[0:1], v[48:49], 0 op_sel_hi:[1,1,0]
	v_pk_fma_f32 v[2:3], v[2:3], v[32:33], 0 op_sel_hi:[1,1,0]
	s_waitcnt lgkmcnt(2)
	v_pk_fma_f32 v[0:1], v[50:51], v[44:45], v[0:1]
	v_pk_fma_f32 v[2:3], v[52:53], v[36:37], v[2:3]
	s_waitcnt lgkmcnt(1)
	v_pk_fma_f32 v[0:1], v[54:55], v[46:47], v[0:1]
	v_lshlrev_b32_e32 v44, 16, v87
	v_and_b32_e32 v45, 0xffff0000, v87
	v_pk_fma_f32 v[2:3], v[56:57], v[40:41], v[2:3]
	v_lshlrev_b32_e32 v32, 16, v86
	v_and_b32_e32 v33, 0xffff0000, v86
	s_waitcnt lgkmcnt(0)
	v_pk_fma_f32 v[0:1], v[58:59], v[44:45], v[0:1]
	v_pk_fma_f32 v[36:37], v[60:61], v[32:33], v[2:3]
	v_mul_f32_e32 v44, 0xbfb8aa3b, v0
	v_mul_f32_e32 v45, 0xbfb8aa3b, v1
	v_mul_f32_e32 v2, 0xbfb8aa3b, v36
	v_exp_f32_e32 v44, v44
	v_exp_f32_e32 v45, v45
	v_exp_f32_e32 v2, v2
	v_mul_f32_e32 v3, 0xbfb8aa3b, v37
	v_exp_f32_e32 v3, v3
	v_add_f32_e32 v44, 1.0, v44
	v_add_f32_e32 v45, 1.0, v45
	v_add_f32_e32 v2, 1.0, v2
	v_rcp_f32_e32 v44, v44
	v_rcp_f32_e32 v45, v45
	v_rcp_f32_e32 v40, v2
	v_add_f32_e32 v2, 1.0, v3
	v_rcp_f32_e32 v97, v97
	v_rcp_f32_e32 v41, v2
	v_pk_mul_f32 v[0:1], v[0:1], v[44:45]
	v_pk_mul_f32 v[14:15], v[14:15], s[36:37] op_sel_hi:[1,0]
	v_pk_mul_f32 v[38:39], v[94:95], v[96:97]
	v_pk_mul_f32 v[4:5], v[4:5], s[36:37] op_sel_hi:[1,0]
	v_pk_mul_f32 v[6:7], v[6:7], v[62:63]
	v_pk_mul_f32 v[2:3], v[0:1], s[36:37] op_sel_hi:[1,0]
	v_pk_mul_f32 v[0:1], v[36:37], v[40:41]
	v_pk_mul_f32 v[34:35], v[34:35], s[36:37] op_sel_hi:[1,0]
	v_pk_mul_f32 v[42:43], v[92:93], s[36:37] op_sel_hi:[1,0]
	v_pk_mul_f32 v[38:39], v[38:39], s[36:37] op_sel_hi:[1,0]
	v_pk_mul_f32 v[32:33], v[6:7], s[36:37] op_sel_hi:[1,0]
	v_cvt_pk_bf16_f32 v44, v26, v27
	v_cvt_pk_bf16_f32 v45, v24, v25
	v_cvt_pk_bf16_f32 v46, v22, v23
	v_cvt_pk_bf16_f32 v47, v20, v21
	ds_write_b128 v85, v[44:47] offset:17408
	v_cvt_pk_bf16_f32 v44, v18, v19
	v_cvt_pk_bf16_f32 v45, v16, v17
	v_cvt_pk_bf16_f32 v46, v12, v13
	v_cvt_pk_bf16_f32 v47, v10, v11
	v_lshlrev_b32_e32 v6, 4, v79
	v_pk_mul_f32 v[0:1], v[0:1], s[36:37] op_sel_hi:[1,0]
	ds_write_b128 v85, v[44:47] offset:17424
	v_cvt_pk_bf16_f32 v44, v14, v15
	v_cvt_pk_bf16_f32 v45, v34, v35
	v_cvt_pk_bf16_f32 v46, v42, v43
	v_cvt_pk_bf16_f32 v47, v38, v39
	v_and_b32_e32 v57, 0x180, v6
	v_mul_f32_e32 v6, v83, v26
	ds_write_b128 v85, v[44:47] offset:17440
	v_cvt_pk_bf16_f32 v44, v4, v5
	v_cvt_pk_bf16_f32 v45, v32, v33
	v_cvt_pk_bf16_f32 v46, v2, v3
	v_cvt_pk_bf16_f32 v47, v0, v1
	v_lshrrev_b32_e32 v56, 5, v79
	v_cvt_pk_bf16_f32 v26, v6, s0
	v_lshlrev_b32_e32 v6, 11, v81
	ds_write_b128 v85, v[44:47] offset:17456
	v_bfe_u32 v85, v30, 2, 3
	v_lshl_add_u32 v6, v56, 9, v6
	v_or_b32_e32 v58, v6, v85
	v_or_b32_e32 v6, v58, v57
	v_ashrrev_i32_e32 v7, 31, v6
	v_lshlrev_b64 v[6:7], 1, v[6:7]
	v_lshl_add_u64 v[36:37], s[66:67], 0, v[6:7]
	v_lshl_add_u64 v[248:249], s[86:87], 0, v[8:9]
	v_lshl_add_u64 v[248:249], v[248:249], 0, s[34:35]
	v_lshl_add_u64 v[248:249], v[248:249], 0, v[28:29]
	v_lshl_add_u64 v[248:249], v[248:249], 0, s[42:43]
	global_load_dwordx4 v[232:235], v[248:249], off
	global_load_dwordx4 v[236:239], v[248:249], off offset:16
	global_load_dwordx4 v[240:243], v[248:249], off offset:32
	global_load_dwordx4 v[244:247], v[248:249], off offset:48
	global_store_short v[36:37], v26, off
	v_lshlrev_b32_e32 v26, 16, v26
	ds_add_f32 v84, v26 offset:36864
	v_mul_f32_e32 v26, v83, v27
	v_or_b32_e32 v59, 8, v57
	v_cvt_pk_bf16_f32 v40, v26, s0
	v_or_b32_e32 v26, v58, v59
	v_ashrrev_i32_e32 v27, 31, v26
	v_lshlrev_b64 v[26:27], 1, v[26:27]
	v_lshl_add_u64 v[36:37], s[66:67], 0, v[26:27]
	global_store_short v[36:37], v40, off
	v_lshlrev_b32_e32 v36, 16, v40
	v_or_b32_e32 v60, 16, v57
	ds_add_f32 v84, v36 offset:36868
	v_or_b32_e32 v36, v58, v60
	v_ashrrev_i32_e32 v37, 31, v36
	v_mul_f32_e32 v24, v83, v24
	v_lshlrev_b64 v[36:37], 1, v[36:37]
	v_cvt_pk_bf16_f32 v24, v24, s0
	v_lshl_add_u64 v[40:41], s[66:67], 0, v[36:37]
	global_store_short v[40:41], v24, off
	v_lshlrev_b32_e32 v24, 16, v24
	ds_add_f32 v84, v24 offset:36872
	v_mul_f32_e32 v24, v83, v25
	v_or_b32_e32 v61, 24, v57
	v_cvt_pk_bf16_f32 v44, v24, s0
	v_or_b32_e32 v24, v58, v61
	v_ashrrev_i32_e32 v25, 31, v24
	v_lshlrev_b64 v[24:25], 1, v[24:25]
	v_lshl_add_u64 v[40:41], s[66:67], 0, v[24:25]
	global_store_short v[40:41], v44, off
	v_lshlrev_b32_e32 v40, 16, v44
	v_or_b32_e32 v62, 32, v57
	ds_add_f32 v84, v40 offset:36876
	v_or_b32_e32 v40, v58, v62
	v_ashrrev_i32_e32 v41, 31, v40
	v_mul_f32_e32 v22, v83, v22
	v_lshlrev_b64 v[40:41], 1, v[40:41]
	v_cvt_pk_bf16_f32 v22, v22, s0
	v_lshl_add_u64 v[44:45], s[66:67], 0, v[40:41]
	global_store_short v[44:45], v22, off
	v_lshlrev_b32_e32 v22, 16, v22
	ds_add_f32 v84, v22 offset:36880
	v_mul_f32_e32 v22, v83, v23
	v_or_b32_e32 v63, 40, v57
	v_cvt_pk_bf16_f32 v46, v22, s0
; DI bf16_t f2bf(float f) { return (bf16_t)(pk2(f, 0.f) & 0xffffu); }
; DI float bf2f(bf16_t h) { return __uint_as_float(((unsigned)h) << 16); }
; DI int fragoff(int row, int k, int KS) { return (((row >> 4) * KS + (k >> 5)) << 9) + (((((k >> 3) & 3) << 4) + (row & 15)) << 3) + (k & 7); }
; DI void mlstm_pre(const Params& p, int ch, char* smem) {
;     ...
;     for (int i = 0; i < 32; ++i) {
;       bf16_t kb = f2bf(a[i] * wgt);
;       o_kwT[fragoff(part * 32 + i, t, 2)] = kb;
;       atomicAdd(&s_kw[part * 32 + i], bf2f(kb));
;     }
	v_or_b32_e32 v22, v58, v63
	v_ashrrev_i32_e32 v23, 31, v22
	v_lshlrev_b64 v[22:23], 1, v[22:23]
	v_lshl_add_u64 v[44:45], s[66:67], 0, v[22:23]
	global_store_short v[44:45], v46, off
	v_lshlrev_b32_e32 v44, 16, v46
	v_or_b32_e32 v64, 48, v57
	ds_add_f32 v84, v44 offset:36884
	v_or_b32_e32 v44, v58, v64
	v_ashrrev_i32_e32 v45, 31, v44
	v_mul_f32_e32 v20, v83, v20
	v_lshlrev_b64 v[44:45], 1, v[44:45]
	v_cvt_pk_bf16_f32 v20, v20, s0
	v_lshl_add_u64 v[46:47], s[66:67], 0, v[44:45]
	global_store_short v[46:47], v20, off
	v_lshlrev_b32_e32 v20, 16, v20
	ds_add_f32 v84, v20 offset:36888
	v_mul_f32_e32 v20, v83, v21
	v_or_b32_e32 v65, 56, v57
	v_cvt_pk_bf16_f32 v48, v20, s0
	v_or_b32_e32 v20, v58, v65
	v_ashrrev_i32_e32 v21, 31, v20
	v_lshlrev_b64 v[20:21], 1, v[20:21]
	v_lshl_add_u64 v[46:47], s[66:67], 0, v[20:21]
	global_store_short v[46:47], v48, off
	v_lshlrev_b32_e32 v46, 16, v48
	v_or_b32_e32 v86, 64, v57
	ds_add_f32 v84, v46 offset:36892
	v_or_b32_e32 v46, v58, v86
	v_ashrrev_i32_e32 v47, 31, v46
	v_mul_f32_e32 v18, v83, v18
	v_lshlrev_b64 v[46:47], 1, v[46:47]
	v_cvt_pk_bf16_f32 v18, v18, s0
	v_lshl_add_u64 v[48:49], s[66:67], 0, v[46:47]
	global_store_short v[48:49], v18, off
	v_lshlrev_b32_e32 v18, 16, v18
	ds_add_f32 v84, v18 offset:36896
	v_mul_f32_e32 v18, v83, v19
	v_or_b32_e32 v87, 0x48, v57
	v_cvt_pk_bf16_f32 v50, v18, s0
	v_or_b32_e32 v18, v58, v87
	v_ashrrev_i32_e32 v19, 31, v18
	v_lshlrev_b64 v[18:19], 1, v[18:19]
	v_lshl_add_u64 v[48:49], s[66:67], 0, v[18:19]
	global_store_short v[48:49], v50, off
	v_lshlrev_b32_e32 v48, 16, v50
	v_or_b32_e32 v88, 0x50, v57
	ds_add_f32 v84, v48 offset:36900
	v_or_b32_e32 v48, v58, v88
	v_ashrrev_i32_e32 v49, 31, v48
	v_mul_f32_e32 v16, v83, v16
	v_lshlrev_b64 v[48:49], 1, v[48:49]
	v_cvt_pk_bf16_f32 v16, v16, s0
	v_lshl_add_u64 v[50:51], s[66:67], 0, v[48:49]
	global_store_short v[50:51], v16, off
	v_lshlrev_b32_e32 v16, 16, v16
	ds_add_f32 v84, v16 offset:36904
	v_mul_f32_e32 v16, v83, v17
	v_or_b32_e32 v89, 0x58, v57
	v_cvt_pk_bf16_f32 v52, v16, s0
	v_or_b32_e32 v16, v58, v89
	v_ashrrev_i32_e32 v17, 31, v16
	v_lshlrev_b64 v[16:17], 1, v[16:17]
	v_lshl_add_u64 v[50:51], s[66:67], 0, v[16:17]
	global_store_short v[50:51], v52, off
	v_lshlrev_b32_e32 v50, 16, v52
	v_or_b32_e32 v90, 0x60, v57
	ds_add_f32 v84, v50 offset:36908
	v_or_b32_e32 v50, v58, v90
	v_ashrrev_i32_e32 v51, 31, v50
	v_mul_f32_e32 v12, v83, v12
	v_lshlrev_b64 v[50:51], 1, v[50:51]
	v_cvt_pk_bf16_f32 v12, v12, s0
	v_lshl_add_u64 v[52:53], s[66:67], 0, v[50:51]
	global_store_short v[52:53], v12, off
	v_lshlrev_b32_e32 v12, 16, v12
	ds_add_f32 v84, v12 offset:36912
	v_mul_f32_e32 v12, v83, v13
	v_or_b32_e32 v91, 0x68, v57
	v_cvt_pk_bf16_f32 v54, v12, s0
	v_or_b32_e32 v12, v58, v91
	v_ashrrev_i32_e32 v13, 31, v12
	v_lshlrev_b64 v[12:13], 1, v[12:13]
	v_lshl_add_u64 v[52:53], s[66:67], 0, v[12:13]
	global_store_short v[52:53], v54, off
	v_lshlrev_b32_e32 v52, 16, v54
	v_or_b32_e32 v92, 0x70, v57
	ds_add_f32 v84, v52 offset:36916
	v_or_b32_e32 v52, v58, v92
	v_ashrrev_i32_e32 v53, 31, v52
	v_mul_f32_e32 v10, v83, v10
	v_lshlrev_b64 v[52:53], 1, v[52:53]
	v_cvt_pk_bf16_f32 v10, v10, s0
	v_lshl_add_u64 v[54:55], s[66:67], 0, v[52:53]
	global_store_short v[54:55], v10, off
	v_lshlrev_b32_e32 v10, 16, v10
	ds_add_f32 v84, v10 offset:36920
	v_mul_f32_e32 v10, v83, v11
	v_or_b32_e32 v94, 0x78, v57
	v_cvt_pk_bf16_f32 v93, v10, s0
	v_or_b32_e32 v10, v58, v94
	v_ashrrev_i32_e32 v11, 31, v10
	v_lshlrev_b64 v[10:11], 1, v[10:11]
	v_lshl_add_u64 v[54:55], s[66:67], 0, v[10:11]
	global_store_short v[54:55], v93, off
	v_lshlrev_b32_e32 v54, 16, v93
	ds_add_f32 v84, v54 offset:36924
	v_lshl_add_u32 v54, v81, 2, v56
	v_lshl_add_u32 v81, v54, 9, v78
	v_or3_b32 v54, v57, v85, v81
	v_ashrrev_i32_e32 v55, 31, v54
	v_mul_f32_e32 v14, v83, v14
	v_lshlrev_b64 v[54:55], 1, v[54:55]
	v_cvt_pk_bf16_f32 v14, v14, s0
	v_lshl_add_u64 v[56:57], s[66:67], 0, v[54:55]
	global_store_short v[56:57], v14, off
	v_lshlrev_b32_e32 v14, 16, v14
	ds_add_f32 v84, v14 offset:36928
	v_mul_f32_e32 v14, v83, v15
	v_cvt_pk_bf16_f32 v58, v14, s0
	v_or3_b32 v14, v59, v85, v81
	v_ashrrev_i32_e32 v15, 31, v14
	v_lshlrev_b64 v[14:15], 1, v[14:15]
	v_lshl_add_u64 v[56:57], s[66:67], 0, v[14:15]
	global_store_short v[56:57], v58, off
	v_lshlrev_b32_e32 v56, 16, v58
	ds_add_f32 v84, v56 offset:36932
	v_or3_b32 v56, v60, v85, v81
	v_ashrrev_i32_e32 v57, 31, v56
	v_mul_f32_e32 v34, v83, v34
	v_lshlrev_b64 v[56:57], 1, v[56:57]
	v_cvt_pk_bf16_f32 v34, v34, s0
	v_lshl_add_u64 v[58:59], s[66:67], 0, v[56:57]
	global_store_short v[58:59], v34, off
	v_lshlrev_b32_e32 v34, 16, v34
	ds_add_f32 v84, v34 offset:36936
	v_mul_f32_e32 v34, v83, v35
	v_cvt_pk_bf16_f32 v60, v34, s0
	v_or3_b32 v34, v61, v85, v81
	v_ashrrev_i32_e32 v35, 31, v34
	v_lshlrev_b64 v[34:35], 1, v[34:35]
	v_lshl_add_u64 v[58:59], s[66:67], 0, v[34:35]
	global_store_short v[58:59], v60, off
	v_lshlrev_b32_e32 v58, 16, v60
	ds_add_f32 v84, v58 offset:36940
	v_or3_b32 v58, v62, v85, v81
	v_ashrrev_i32_e32 v59, 31, v58
	v_mul_f32_e32 v42, v83, v42
	v_lshlrev_b64 v[58:59], 1, v[58:59]
	v_cvt_pk_bf16_f32 v42, v42, s0
	v_lshl_add_u64 v[60:61], s[66:67], 0, v[58:59]
	global_store_short v[60:61], v42, off
	v_lshlrev_b32_e32 v42, 16, v42
	ds_add_f32 v84, v42 offset:36944
	v_mul_f32_e32 v42, v83, v43
	v_cvt_pk_bf16_f32 v62, v42, s0
	v_or3_b32 v42, v63, v85, v81
	v_ashrrev_i32_e32 v43, 31, v42
	v_lshlrev_b64 v[42:43], 1, v[42:43]
	v_lshl_add_u64 v[60:61], s[66:67], 0, v[42:43]
	global_store_short v[60:61], v62, off
	v_lshlrev_b32_e32 v60, 16, v62
	ds_add_f32 v84, v60 offset:36948
	v_or3_b32 v60, v64, v85, v81
	v_ashrrev_i32_e32 v61, 31, v60
; DI bf16_t f2bf(float f) { return (bf16_t)(pk2(f, 0.f) & 0xffffu); }
; DI float bf2f(bf16_t h) { return __uint_as_float(((unsigned)h) << 16); }
; DI int fragoff(int row, int k, int KS) { return (((row >> 4) * KS + (k >> 5)) << 9) + (((((k >> 3) & 3) << 4) + (row & 15)) << 3) + (k & 7); }
; DI void mlstm_pre(const Params& p, int ch, char* smem) {
;     ...
;     for (int i = 0; i < 32; ++i) {
;       bf16_t kb = f2bf(a[i] * wgt);
;       o_kwT[fragoff(part * 32 + i, t, 2)] = kb;
;       atomicAdd(&s_kw[part * 32 + i], bf2f(kb));
;     }
;     const uint4* vsrc = (const uint4*)(P + (size_t)(tok0 + t) * 4096 + 3072 + h * 128 + part * 32);
; #pragma unroll
;     for (int q = 0; q < 4; ++q) {
;       uint4 v = vsrc[q];
;       const unsigned uu[4] = {v.x, v.y, v.z, v.w};
; #pragma unroll
;       for (int e = 0; e < 4; ++e) {
;         o_vT[fragoff(part * 32 + 8 * q + 2 * e, t, 2)] = (bf16_t)(uu[e] & 0xffffu);
;         o_vT[fragoff(part * 32 + 8 * q + 2 * e + 1, t, 2)] = (bf16_t)(uu[e] >> 16);
;       }
;     }
	v_mul_f32_e32 v38, v83, v38
	v_lshlrev_b64 v[60:61], 1, v[60:61]
	v_cvt_pk_bf16_f32 v38, v38, s0
	v_lshl_add_u64 v[62:63], s[66:67], 0, v[60:61]
	global_store_short v[62:63], v38, off
	v_lshlrev_b32_e32 v38, 16, v38
	ds_add_f32 v84, v38 offset:36952
	v_mul_f32_e32 v38, v83, v39
	v_cvt_pk_bf16_f32 v64, v38, s0
	v_or3_b32 v38, v65, v85, v81
	v_ashrrev_i32_e32 v39, 31, v38
	v_lshlrev_b64 v[38:39], 1, v[38:39]
	v_lshl_add_u64 v[62:63], s[66:67], 0, v[38:39]
	global_store_short v[62:63], v64, off
	v_lshlrev_b32_e32 v62, 16, v64
	ds_add_f32 v84, v62 offset:36956
	v_or3_b32 v62, v86, v85, v81
	v_ashrrev_i32_e32 v63, 31, v62
	v_mul_f32_e32 v4, v83, v4
	v_lshlrev_b64 v[62:63], 1, v[62:63]
	v_cvt_pk_bf16_f32 v4, v4, s0
	v_lshl_add_u64 v[64:65], s[66:67], 0, v[62:63]
	global_store_short v[64:65], v4, off
	v_lshlrev_b32_e32 v4, 16, v4
	ds_add_f32 v84, v4 offset:36960
	v_mul_f32_e32 v4, v83, v5
	v_cvt_pk_bf16_f32 v86, v4, s0
	v_or3_b32 v4, v87, v85, v81
	v_ashrrev_i32_e32 v5, 31, v4
	v_lshlrev_b64 v[4:5], 1, v[4:5]
	v_lshl_add_u64 v[64:65], s[66:67], 0, v[4:5]
	global_store_short v[64:65], v86, off
	v_lshlrev_b32_e32 v64, 16, v86
	ds_add_f32 v84, v64 offset:36964
	v_or3_b32 v64, v88, v85, v81
	v_ashrrev_i32_e32 v65, 31, v64
	v_mul_f32_e32 v32, v83, v32
	v_lshlrev_b64 v[64:65], 1, v[64:65]
	v_cvt_pk_bf16_f32 v32, v32, s0
	v_lshl_add_u64 v[86:87], s[66:67], 0, v[64:65]
	global_store_short v[86:87], v32, off
	v_lshlrev_b32_e32 v32, 16, v32
	ds_add_f32 v84, v32 offset:36968
	v_mul_f32_e32 v32, v83, v33
	v_cvt_pk_bf16_f32 v88, v32, s0
	v_or3_b32 v32, v89, v85, v81
	v_ashrrev_i32_e32 v33, 31, v32
	v_lshlrev_b64 v[32:33], 1, v[32:33]
	v_lshl_add_u64 v[86:87], s[66:67], 0, v[32:33]
	global_store_short v[86:87], v88, off
	v_lshlrev_b32_e32 v86, 16, v88
	ds_add_f32 v84, v86 offset:36972
	v_or3_b32 v86, v90, v85, v81
	v_ashrrev_i32_e32 v87, 31, v86
	v_mul_f32_e32 v2, v83, v2
	v_lshlrev_b64 v[86:87], 1, v[86:87]
	v_cvt_pk_bf16_f32 v2, v2, s0
	v_lshl_add_u64 v[88:89], s[66:67], 0, v[86:87]
	global_store_short v[88:89], v2, off
	v_lshlrev_b32_e32 v2, 16, v2
	ds_add_f32 v84, v2 offset:36976
	v_mul_f32_e32 v2, v83, v3
	v_cvt_pk_bf16_f32 v90, v2, s0
	v_or3_b32 v2, v91, v85, v81
	v_ashrrev_i32_e32 v3, 31, v2
	v_lshlrev_b64 v[88:89], 1, v[2:3]
	v_lshl_add_u64 v[2:3], s[66:67], 0, v[88:89]
	global_store_short v[2:3], v90, off
	v_lshlrev_b32_e32 v2, 16, v90
	ds_add_f32 v84, v2 offset:36980
	v_or3_b32 v2, v92, v85, v81
	v_ashrrev_i32_e32 v3, 31, v2
	v_mul_f32_e32 v0, v83, v0
	v_lshlrev_b64 v[90:91], 1, v[2:3]
	v_cvt_pk_bf16_f32 v0, v0, s0
	v_lshl_add_u64 v[2:3], s[66:67], 0, v[90:91]
	global_store_short v[2:3], v0, off
	v_lshlrev_b32_e32 v0, 16, v0
	ds_add_f32 v84, v0 offset:36984
	v_mul_f32_e32 v0, v83, v1
	v_cvt_pk_bf16_f32 v2, v0, s0
	v_or3_b32 v0, v94, v85, v81
	v_ashrrev_i32_e32 v1, 31, v0
	v_lshlrev_b64 v[92:93], 1, v[0:1]
	v_lshl_add_u64 v[0:1], s[66:67], 0, v[92:93]
	global_store_short v[0:1], v2, off
	v_lshlrev_b32_e32 v0, 16, v2
	ds_add_f32 v84, v0 offset:36988
	v_lshl_add_u64 v[0:1], s[86:87], 0, v[8:9]
	v_lshl_add_u64 v[0:1], v[0:1], 0, s[34:35]
	v_lshl_add_u64 v[8:9], v[0:1], 0, v[28:29]
	s_movk_i32 s8, 0x1000
	v_add_co_u32_e64 v0, s[8:9], s8, v8
	v_lshl_add_u64 v[6:7], s[64:65], 0, v[6:7]
	s_nop 0
	v_addc_co_u32_e64 v1, s[8:9], 0, v9, s[8:9]
	s_nop 0
	v_lshl_add_u64 v[8:9], v[8:9], 0, s[42:43]
	v_lshl_add_u64 v[4:5], s[64:65], 0, v[4:5]
	s_waitcnt vmcnt(32)
	v_mov_b32_e32 v0, v232
	v_mov_b32_e32 v1, v233
	v_mov_b32_e32 v2, v234
	v_mov_b32_e32 v3, v235
	global_store_short v[6:7], v0, off
	v_lshl_add_u64 v[6:7], s[64:65], 0, v[26:27]
	global_store_short_d16_hi v[6:7], v0, off
	v_lshl_add_u64 v[6:7], s[64:65], 0, v[36:37]
	global_store_short v[6:7], v1, off
	v_lshl_add_u64 v[6:7], s[64:65], 0, v[24:25]
	global_store_short_d16_hi v[6:7], v1, off
	v_lshl_add_u64 v[0:1], s[64:65], 0, v[40:41]
	global_store_short v[0:1], v2, off
	v_lshl_add_u64 v[0:1], s[64:65], 0, v[22:23]
	global_store_short_d16_hi v[0:1], v2, off
	v_lshl_add_u64 v[0:1], s[64:65], 0, v[44:45]
	global_store_short v[0:1], v3, off
	v_lshl_add_u64 v[0:1], s[64:65], 0, v[20:21]
	global_store_short_d16_hi v[0:1], v3, off
	s_nop 0
	v_lshl_add_u64 v[6:7], s[64:65], 0, v[46:47]
	v_and_b32_e32 v21, 31, v30
	v_mov_b32_e32 v0, v236
	v_mov_b32_e32 v1, v237
	v_mov_b32_e32 v2, v238
	v_mov_b32_e32 v3, v239
	global_store_short v[6:7], v0, off
	v_lshl_add_u64 v[6:7], s[64:65], 0, v[18:19]
	global_store_short_d16_hi v[6:7], v0, off
	v_lshl_add_u64 v[6:7], s[64:65], 0, v[48:49]
	global_store_short v[6:7], v1, off
	v_lshl_add_u64 v[6:7], s[64:65], 0, v[16:17]
	global_store_short_d16_hi v[6:7], v1, off
	v_lshl_add_u64 v[0:1], s[64:65], 0, v[50:51]
	global_store_short v[0:1], v2, off
	v_lshl_add_u64 v[0:1], s[64:65], 0, v[12:13]
	global_store_short_d16_hi v[0:1], v2, off
	v_lshl_add_u64 v[0:1], s[64:65], 0, v[52:53]
	global_store_short v[0:1], v3, off
	v_lshl_add_u64 v[0:1], s[64:65], 0, v[10:11]
	global_store_short_d16_hi v[0:1], v3, off
	s_nop 0
	v_lshl_add_u64 v[6:7], s[64:65], 0, v[54:55]
	v_bfe_u32 v16, v30, 6, 1
	v_lshl_or_b32 v17, v16, 5, v21
	v_mov_b32_e32 v0, v240
	v_mov_b32_e32 v1, v241
	v_mov_b32_e32 v2, v242
	v_mov_b32_e32 v3, v243
	global_store_short v[6:7], v0, off
	v_lshl_add_u64 v[6:7], s[64:65], 0, v[14:15]
	global_store_short_d16_hi v[6:7], v0, off
	v_lshl_add_u64 v[6:7], s[64:65], 0, v[56:57]
	global_store_short v[6:7], v1, off
	v_lshl_add_u64 v[6:7], s[64:65], 0, v[34:35]
	global_store_short_d16_hi v[6:7], v1, off
	v_lshl_add_u64 v[0:1], s[64:65], 0, v[58:59]
	global_store_short v[0:1], v2, off
	v_lshl_add_u64 v[0:1], s[64:65], 0, v[42:43]
	global_store_short_d16_hi v[0:1], v2, off
	v_lshl_add_u64 v[0:1], s[64:65], 0, v[60:61]
	global_store_short v[0:1], v3, off
	v_lshl_add_u64 v[0:1], s[64:65], 0, v[38:39]
	global_store_short_d16_hi v[0:1], v3, off
	s_nop 0
	v_lshl_add_u64 v[6:7], s[64:65], 0, v[62:63]
	v_mov_b32_e32 v0, v244
	v_mov_b32_e32 v1, v245
	v_mov_b32_e32 v2, v246
	v_mov_b32_e32 v3, v247
	global_store_short_d16_hi v[4:5], v0, off
	v_lshl_add_u64 v[4:5], s[64:65], 0, v[64:65]
	global_store_short v[4:5], v1, off
	v_lshl_add_u64 v[4:5], s[64:65], 0, v[32:33]
	global_store_short v[6:7], v0, off
	global_store_short_d16_hi v[4:5], v1, off
	v_lshl_add_u64 v[0:1], s[64:65], 0, v[86:87]
	global_store_short v[0:1], v2, off
	v_lshl_add_u64 v[0:1], s[64:65], 0, v[88:89]
	global_store_short_d16_hi v[0:1], v2, off
	v_lshl_add_u64 v[0:1], s[64:65], 0, v[90:91]
	global_store_short v[0:1], v3, off
	v_lshl_add_u64 v[0:1], s[64:65], 0, v[92:93]
	global_store_short_d16_hi v[0:1], v3, off
	v_lshrrev_b32_e32 v1, 1, v30
	v_bfi_b32 v0, s79, v79, v30
	v_and_b32_e32 v4, 16, v1
	v_mad_u64_u32 v[18:19], s[8:9], v0, s75, v[4:5]
	s_waitcnt lgkmcnt(0)
	s_barrier
; #define MFMA32(a, b, c) __builtin_amdgcn_mfma_f32_32x32x16_bf16((a), (b), (c), 0, 0, 0)
; DI int crow32(int r, int half) { return (r & 3) + 8 * (r >> 2) + 4 * half; }
; DI void mlstm_pre(const Params& p, int ch, char* smem) {
;     ...
;   __syncthreads();
;   {
;     const int ti = wave >> 1, tj = wave & 1;
;     f32x16 acc;
; #pragma unroll
;     for (int r = 0; r < 16; ++r) acc[r] = 0.f;
; #pragma unroll
;     for (int s = 0; s < 8; ++s) {
;       const int ko = s * 16 + (lane >> 5) * 8;
;       bf16x8 bk = *(const bf16x8*)(ks + (tj * 32 + (lane & 31)) * 136 + ko);
;       bf16x8 aq = *(const bf16x8*)(qs + (ti * 32 + (lane & 31)) * 136 + ko);
;       acc = MFMA32(aq, bk, acc);
;     }
;     const int j = tj * 32 + (lane & 31);
;     const float cj = s_li[j] - s_bc[j];
; #pragma unroll
;     for (int r = 0; r < 16; ++r) {
;       const int i = ti * 32 + crow32(r, lane >> 5);
;       float pv = (i >= j) ? acc[r] * __expf(s_bc[i] + cj - s_mt[i]) : 0.f;
	ds_read_b128 v[0:3], v18
	v_mad_u32_u24 v19, v17, s75, v4
	ds_read_b128 v[4:7], v19 offset:17408
	ds_read_b128 v[22:25], v19 offset:17440
	ds_read_b128 v[32:35], v18 offset:32
	s_waitcnt lgkmcnt(2)
	v_mfma_f32_32x32x16_bf16 v[0:15], v[0:3], v[4:7], 0
	s_waitcnt lgkmcnt(0)
	v_mfma_f32_32x32x16_bf16 v[0:15], v[32:35], v[22:25], v[0:15]
	ds_read_b128 v[22:25], v18 offset:64
	ds_read_b128 v[32:35], v19 offset:17472
	ds_read_b128 v[36:39], v19 offset:17504
	ds_read_b128 v[40:43], v18 offset:96
	s_waitcnt lgkmcnt(2)
	v_mfma_f32_32x32x16_bf16 v[0:15], v[22:25], v[32:35], v[0:15]
	s_waitcnt lgkmcnt(0)
	v_mfma_f32_32x32x16_bf16 v[0:15], v[40:43], v[36:39], v[0:15]
	ds_read_b128 v[22:25], v18 offset:128
	ds_read_b128 v[32:35], v19 offset:17536
	ds_read_b128 v[36:39], v19 offset:17568
	ds_read_b128 v[40:43], v18 offset:160
	s_waitcnt lgkmcnt(2)
	v_mfma_f32_32x32x16_bf16 v[0:15], v[22:25], v[32:35], v[0:15]
	s_waitcnt lgkmcnt(0)
	v_mfma_f32_32x32x16_bf16 v[0:15], v[40:43], v[36:39], v[0:15]
	ds_read_b128 v[22:25], v18 offset:192
	ds_read_b128 v[32:35], v19 offset:17600
	ds_read_b128 v[36:39], v19 offset:17632
	ds_read_b128 v[40:43], v18 offset:224
	v_mul_i32_i24_e32 v18, 0xfffffef4, v17
	v_mad_u32_u24 v18, v17, s75, v18
	ds_read2st64_b32 v[18:19], v18 offset0:136 offset1:138
	s_waitcnt lgkmcnt(0)
	v_sub_f32_e32 v19, v18, v19
	v_mfma_f32_32x32x16_bf16 v[0:15], v[22:25], v[32:35], v[0:15]
	v_lshrrev_b32_e32 v18, 3, v30
	v_and_b32_e32 v22, 0xffffffe0, v79
	v_and_b32_e32 v23, 4, v18
	v_or_b32_e32 v20, v23, v22
	v_cmp_ge_i32_e64 s[8:9], v20, v17
	v_mov_b32_e32 v24, 0
	v_lshlrev_b32_e32 v18, 2, v20
	v_mfma_f32_32x32x16_bf16 v[0:15], v[40:43], v[36:39], v[0:15]
	s_and_saveexec_b64 s[10:11], s[8:9]
	s_cbranch_execz .LBB0_406
	ds_read2st64_b32 v[24:25], v18 offset0:138 offset1:140
	s_waitcnt lgkmcnt(0)
	v_add_f32_e32 v24, v19, v24
	v_sub_f32_e32 v24, v24, v25
	v_mul_f32_e32 v24, 0x3fb8aa3b, v24
	v_exp_f32_e32 v24, v24
	s_nop 3
	v_mul_f32_e32 v24, v0, v24
